# gu GEMM as 160x(2x128) pair tiles sharing each A K-tile across two column tiles, static priority for odd hardware wave slots in GEMM phases
# speedup vs baseline: 1.1676x; 1.0098x over previous
.LBB0_191:
	s_andn2_b64 vcc, exec, s[2:3]
	s_cbranch_vccnz .LBB0_247
	v_readlane_b32 s10, v164, 0
	v_readlane_b32 s11, v162, 14
	v_readlane_b32 s16, v163, 15
	v_readlane_b32 s17, v163, 16
	v_readlane_b32 s18, v163, 5
	v_readlane_b32 s19, v163, 6
	s_mul_i32 s4, s34, 0x1600000
	s_add_u32 s18, s18, s4
	s_addc_u32 s19, s19, 0
	s_movk_i32 s42, 0x800
	v_and_b32_e32 v220, 63, v128
	v_lshrrev_b32_e32 v221, 6, v128
	v_and_b32_e32 v222, 15, v220
	v_lshrrev_b32_e32 v223, 4, v220
	v_readfirstlane_b32 s40, v221
	v_bfe_u32 v224, v222, 1, 3
	s_lshl_b32 s13, s40, 10
	s_and_b32 s36, s40, 1
	s_lshr_b32 s35, s40, 1
	v_xor_b32_e32 v225, v223, v224
	v_lshlrev_b32_e32 v225, 4, v225
	s_mul_i32 s4, s35, 0x50
	v_add_u32_e32 v226, s4, v222
	v_lshl_add_u32 v116, v226, 7, v225
	v_xor_b32_e32 v118, 64, v116
	s_lshl_b32 s4, s36, 6
	v_add_u32_e32 v227, s4, v222
	v_lshl_add_u32 v119, v227, 7, v225
	v_xor_b32_e32 v160, 64, v119
	v_and_b32_e32 v228, 7, v220
	v_lshrrev_b32_e32 v229, 3, v220
	v_xor_b32_e32 v230, v228, v223
	s_lshl_b32 s4, s36, 2
	v_xor_b32_e32 v230, s4, v230
	v_lshlrev_b32_e32 v230, 4, v230
	s_lshl_b32 s4, s40, 3
	v_add_u32_e32 v231, s4, v229
	v_mad_u32_u24 v161, v231, s42, v230
	v_bfe_u32 v232, v231, 2, 2
	v_and_b32_e32 v233, 3, v231
	v_lshrrev_b32_e32 v234, 4, v231
	v_lshl_add_u32 v232, v232, 3, v233
	s_movk_i32 s4, 0xb00
	v_mad_u32_u24 v232, v234, s4, v232
	v_mad_u32_u24 v165, v232, s42, v230
	v_mul_u32_u24_e32 v167, 0x1600, v226
	v_lshl_add_u32 v167, v223, 4, v167
	s_lshl_b32 s4, s36, 6
	v_add_u32_e32 v167, s4, v167
	s_cmp_ge_u32 s10, 0x580
	s_cbranch_scc1 .Lggu0_done
	s_getreg_b32 s4, hwreg(HW_REG_HW_ID, 0, 4)
	s_and_b32 s4, s4, 1
	s_cmp_eq_u32 s4, 0
	s_cbranch_scc1 .Lggu0_noprio
	s_setprio 1
.Lggu0_noprio:
	s_and_b32 s4, s10, 7
	s_lshl_b32 s4, s4, 3
	s_bfe_u32 s32, s10, 0x30003
	s_or_b32 s4, s4, s32
	s_mul_i32 s4, s4, 0x50000
	s_add_u32 s2, s16, s4
	s_addc_u32 s3, s17, 0
	s_lshr_b32 s4, s10, 6
	s_mul_i32 s4, s4, 0x40000
	s_add_u32 s6, s18, s4
	s_addc_u32 s7, s19, 0
	s_add_u32 m0, s13, 0x0
	s_nop 0
	global_load_lds_dwordx4 v161, s[2:3]
	s_add_u32 m0, s13, 0x1000
	v_add_u32_e32 v166, 0x10000, v161
	global_load_lds_dwordx4 v166, s[2:3]
	s_add_u32 m0, s13, 0x2000
	v_add_u32_e32 v166, 0x20000, v161
	global_load_lds_dwordx4 v166, s[2:3]
	s_add_u32 m0, s13, 0x3000
	v_add_u32_e32 v166, 0x30000, v161
	global_load_lds_dwordx4 v166, s[2:3]
	s_add_u32 m0, s13, 0x4000
	v_add_u32_e32 v166, 0x40000, v161
	global_load_lds_dwordx4 v166, s[2:3]
	s_add_u32 m0, s13, 0x5000
	s_nop 0
	global_load_lds_dwordx4 v165, s[6:7]
	s_add_u32 m0, s13, 0x6000
	v_add_u32_e32 v166, 0x2000, v165
	global_load_lds_dwordx4 v166, s[6:7]
	s_add_u32 m0, s13, 0x7000
	v_add_u32_e32 v166, 0x10000, v165
	global_load_lds_dwordx4 v166, s[6:7]
	s_add_u32 m0, s13, 0x8000
	v_add_u32_e32 v166, 0x12000, v165
	global_load_lds_dwordx4 v166, s[6:7]
	s_add_u32 s24, s6, 0x20000
	s_addc_u32 s25, s7, 0
	s_add_u32 s2, s2, 0x80
	s_addc_u32 s3, s3, 0
	s_add_u32 s6, s6, 0x80
	s_addc_u32 s7, s7, 0
.Lggu0_tile:
	v_mov_b32_e32 v0, 0
	v_mov_b32_e32 v1, 0
	v_mov_b32_e32 v2, 0
	v_mov_b32_e32 v3, 0
	v_mov_b32_e32 v4, 0
	v_mov_b32_e32 v5, 0
	v_mov_b32_e32 v6, 0
	v_mov_b32_e32 v7, 0
	v_mov_b32_e32 v8, 0
	v_mov_b32_e32 v9, 0
	v_mov_b32_e32 v10, 0
	v_mov_b32_e32 v11, 0
	v_mov_b32_e32 v12, 0
	v_mov_b32_e32 v13, 0
	v_mov_b32_e32 v14, 0
	v_mov_b32_e32 v15, 0
	v_mov_b32_e32 v16, 0
	v_mov_b32_e32 v17, 0
	v_mov_b32_e32 v18, 0
	v_mov_b32_e32 v19, 0
	v_mov_b32_e32 v20, 0
	v_mov_b32_e32 v21, 0
	v_mov_b32_e32 v22, 0
	v_mov_b32_e32 v23, 0
	v_mov_b32_e32 v24, 0
	v_mov_b32_e32 v25, 0
	v_mov_b32_e32 v26, 0
	v_mov_b32_e32 v27, 0
	v_mov_b32_e32 v28, 0
	v_mov_b32_e32 v29, 0
	v_mov_b32_e32 v30, 0
	v_mov_b32_e32 v31, 0
	v_mov_b32_e32 v32, 0
	v_mov_b32_e32 v33, 0
	v_mov_b32_e32 v34, 0
	v_mov_b32_e32 v35, 0
	v_mov_b32_e32 v36, 0
	v_mov_b32_e32 v37, 0
	v_mov_b32_e32 v38, 0
	v_mov_b32_e32 v39, 0
	v_mov_b32_e32 v40, 0
	v_mov_b32_e32 v41, 0
	v_mov_b32_e32 v42, 0
	v_mov_b32_e32 v43, 0
	v_mov_b32_e32 v44, 0
	v_mov_b32_e32 v45, 0
	v_mov_b32_e32 v46, 0
	v_mov_b32_e32 v47, 0
	v_mov_b32_e32 v48, 0
	v_mov_b32_e32 v49, 0
	v_mov_b32_e32 v50, 0
	v_mov_b32_e32 v51, 0
	v_mov_b32_e32 v52, 0
	v_mov_b32_e32 v53, 0
	v_mov_b32_e32 v54, 0
	v_mov_b32_e32 v55, 0
	v_mov_b32_e32 v56, 0
	v_mov_b32_e32 v57, 0
	v_mov_b32_e32 v58, 0
	v_mov_b32_e32 v59, 0
	v_mov_b32_e32 v60, 0
	v_mov_b32_e32 v61, 0
	v_mov_b32_e32 v62, 0
	v_mov_b32_e32 v63, 0
	v_mov_b32_e32 v64, 0
	v_mov_b32_e32 v65, 0
	v_mov_b32_e32 v66, 0
	v_mov_b32_e32 v67, 0
	v_mov_b32_e32 v68, 0
	v_mov_b32_e32 v69, 0
	v_mov_b32_e32 v70, 0
	v_mov_b32_e32 v71, 0
	v_mov_b32_e32 v72, 0
	v_mov_b32_e32 v73, 0
	v_mov_b32_e32 v74, 0
	v_mov_b32_e32 v75, 0
	v_mov_b32_e32 v76, 0
	v_mov_b32_e32 v77, 0
	v_mov_b32_e32 v78, 0
	v_mov_b32_e32 v79, 0
	v_mov_b32_e32 v80, 0
	v_mov_b32_e32 v81, 0
	v_mov_b32_e32 v82, 0
	v_mov_b32_e32 v83, 0
	v_mov_b32_e32 v84, 0
	v_mov_b32_e32 v85, 0
	v_mov_b32_e32 v86, 0
	v_mov_b32_e32 v87, 0
	v_mov_b32_e32 v88, 0
	v_mov_b32_e32 v89, 0
	v_mov_b32_e32 v90, 0
	v_mov_b32_e32 v91, 0
	v_mov_b32_e32 v92, 0
	v_mov_b32_e32 v93, 0
	v_mov_b32_e32 v94, 0
	v_mov_b32_e32 v95, 0
	v_mov_b32_e32 v96, 0
	v_mov_b32_e32 v97, 0
	v_mov_b32_e32 v98, 0
	v_mov_b32_e32 v99, 0
	v_mov_b32_e32 v100, 0
	v_mov_b32_e32 v101, 0
	v_mov_b32_e32 v102, 0
	v_mov_b32_e32 v103, 0
	v_mov_b32_e32 v104, 0
	v_mov_b32_e32 v105, 0
	v_mov_b32_e32 v106, 0
	v_mov_b32_e32 v107, 0
	v_mov_b32_e32 v108, 0
	v_mov_b32_e32 v109, 0
	v_mov_b32_e32 v110, 0
	v_mov_b32_e32 v111, 0
	v_mov_b32_e32 v112, 0
	v_mov_b32_e32 v113, 0
	v_mov_b32_e32 v114, 0
	v_mov_b32_e32 v115, 0
	v_mov_b32_e32 v120, 0
	v_mov_b32_e32 v121, 0
	v_mov_b32_e32 v122, 0
	v_mov_b32_e32 v123, 0
	v_mov_b32_e32 v124, 0
	v_mov_b32_e32 v125, 0
	v_mov_b32_e32 v126, 0
	v_mov_b32_e32 v127, 0
	v_mov_b32_e32 v140, 0
	v_mov_b32_e32 v141, 0
	v_mov_b32_e32 v142, 0
	v_mov_b32_e32 v143, 0
	v_mov_b32_e32 v144, 0
	v_mov_b32_e32 v145, 0
	v_mov_b32_e32 v146, 0
	v_mov_b32_e32 v147, 0
	v_mov_b32_e32 v148, 0
	v_mov_b32_e32 v149, 0
	v_mov_b32_e32 v150, 0
	v_mov_b32_e32 v151, 0
	v_mov_b32_e32 v152, 0
	v_mov_b32_e32 v153, 0
	v_mov_b32_e32 v154, 0
	v_mov_b32_e32 v155, 0
	v_mov_b32_e32 v156, 0
	v_mov_b32_e32 v157, 0
	v_mov_b32_e32 v158, 0
	v_mov_b32_e32 v159, 0
	v_mov_b32_e32 v168, 0
	v_mov_b32_e32 v169, 0
	v_mov_b32_e32 v170, 0
	v_mov_b32_e32 v171, 0
	v_mov_b32_e32 v172, 0
	v_mov_b32_e32 v173, 0
	v_mov_b32_e32 v174, 0
	v_mov_b32_e32 v175, 0
	v_mov_b32_e32 v176, 0
	v_mov_b32_e32 v177, 0
	v_mov_b32_e32 v178, 0
	v_mov_b32_e32 v179, 0
	v_mov_b32_e32 v180, 0
	v_mov_b32_e32 v181, 0
	v_mov_b32_e32 v182, 0
	v_mov_b32_e32 v183, 0
	s_add_u32 s14, s10, s11
	s_min_u32 s14, s14, 0x57f
	s_and_b32 s4, s14, 7
	s_lshl_b32 s4, s4, 3
	s_bfe_u32 s32, s14, 0x30003
	s_or_b32 s4, s4, s32
	s_mul_i32 s4, s4, 0x50000
	s_add_u32 s20, s16, s4
	s_addc_u32 s21, s17, 0
	s_lshr_b32 s4, s14, 6
	s_mul_i32 s4, s4, 0x40000
	s_add_u32 s22, s18, s4
	s_addc_u32 s23, s19, 0
	s_movk_i32 s12, 0x8
.Lggu0_pair:
	s_waitcnt vmcnt(0)
	s_barrier
	ds_read_b128 v[184:187], v116 offset:0
	ds_read_b128 v[204:207], v119 offset:20480
	ds_read_b128 v[208:211], v119 offset:22528
	ds_read_b128 v[212:215], v119 offset:24576
	ds_read_b128 v[216:219], v119 offset:26624
	ds_read_b128 v[188:191], v116 offset:2048
	ds_read_b128 v[192:195], v116 offset:4096
	ds_read_b128 v[196:199], v116 offset:6144
	ds_read_b128 v[200:203], v116 offset:8192
	s_waitcnt lgkmcnt(7)
	v_mfma_f32_16x16x32_bf16 v[0:3], v[204:207], v[184:187], v[0:3]
	s_add_u32 m0, s13, 0x9000
	s_nop 0
	global_load_lds_dwordx4 v165, s[24:25]
	s_waitcnt lgkmcnt(6)
	v_mfma_f32_16x16x32_bf16 v[4:7], v[208:211], v[184:187], v[4:7]
	s_add_u32 m0, s13, 0xa000
	v_add_u32_e32 v166, 0x2000, v165
	global_load_lds_dwordx4 v166, s[24:25]
	s_waitcnt lgkmcnt(5)
	v_mfma_f32_16x16x32_bf16 v[8:11], v[212:215], v[184:187], v[8:11]
	s_add_u32 m0, s13, 0xb000
	v_add_u32_e32 v166, 0x10000, v165
	global_load_lds_dwordx4 v166, s[24:25]
	s_waitcnt lgkmcnt(4)
	v_mfma_f32_16x16x32_bf16 v[12:15], v[216:219], v[184:187], v[12:15]
	s_add_u32 m0, s13, 0xc000
	v_add_u32_e32 v166, 0x12000, v165
	global_load_lds_dwordx4 v166, s[24:25]
	ds_read_b128 v[220:223], v118 offset:0
	ds_read_b128 v[240:243], v160 offset:20480
	ds_read_b128 v[244:247], v160 offset:22528
	ds_read_b128 v[248:251], v160 offset:24576
	ds_read_b128 v[252:255], v160 offset:26624
	s_waitcnt lgkmcnt(8)
	v_mfma_f32_16x16x32_bf16 v[16:19], v[204:207], v[188:191], v[16:19]
	v_mfma_f32_16x16x32_bf16 v[20:23], v[208:211], v[188:191], v[20:23]
	v_mfma_f32_16x16x32_bf16 v[24:27], v[212:215], v[188:191], v[24:27]
	v_mfma_f32_16x16x32_bf16 v[28:31], v[216:219], v[188:191], v[28:31]
	ds_read_b128 v[224:227], v118 offset:2048
	ds_read_b128 v[228:231], v118 offset:4096
	ds_read_b128 v[232:235], v118 offset:6144
	ds_read_b128 v[236:239], v118 offset:8192
	s_waitcnt lgkmcnt(11)
	v_mfma_f32_16x16x32_bf16 v[32:35], v[204:207], v[192:195], v[32:35]
	v_mfma_f32_16x16x32_bf16 v[36:39], v[208:211], v[192:195], v[36:39]
	v_mfma_f32_16x16x32_bf16 v[40:43], v[212:215], v[192:195], v[40:43]
	v_mfma_f32_16x16x32_bf16 v[44:47], v[216:219], v[192:195], v[44:47]
	s_waitcnt lgkmcnt(10)
	v_mfma_f32_16x16x32_bf16 v[48:51], v[204:207], v[196:199], v[48:51]
	v_mfma_f32_16x16x32_bf16 v[52:55], v[208:211], v[196:199], v[52:55]
	v_mfma_f32_16x16x32_bf16 v[56:59], v[212:215], v[196:199], v[56:59]
	v_mfma_f32_16x16x32_bf16 v[60:63], v[216:219], v[196:199], v[60:63]
	s_waitcnt lgkmcnt(9)
	v_mfma_f32_16x16x32_bf16 v[64:67], v[204:207], v[200:203], v[64:67]
	v_mfma_f32_16x16x32_bf16 v[68:71], v[208:211], v[200:203], v[68:71]
	v_mfma_f32_16x16x32_bf16 v[72:75], v[212:215], v[200:203], v[72:75]
	v_mfma_f32_16x16x32_bf16 v[76:79], v[216:219], v[200:203], v[76:79]
	s_waitcnt lgkmcnt(7)
	v_mfma_f32_16x16x32_bf16 v[0:3], v[240:243], v[220:223], v[0:3]
	s_waitcnt lgkmcnt(6)
	v_mfma_f32_16x16x32_bf16 v[4:7], v[244:247], v[220:223], v[4:7]
	s_waitcnt lgkmcnt(5)
	v_mfma_f32_16x16x32_bf16 v[8:11], v[248:251], v[220:223], v[8:11]
	s_waitcnt lgkmcnt(4)
	v_mfma_f32_16x16x32_bf16 v[12:15], v[252:255], v[220:223], v[12:15]
	s_waitcnt lgkmcnt(3)
	v_mfma_f32_16x16x32_bf16 v[16:19], v[240:243], v[224:227], v[16:19]
	v_mfma_f32_16x16x32_bf16 v[20:23], v[244:247], v[224:227], v[20:23]
	v_mfma_f32_16x16x32_bf16 v[24:27], v[248:251], v[224:227], v[24:27]
	v_mfma_f32_16x16x32_bf16 v[28:31], v[252:255], v[224:227], v[28:31]
	s_waitcnt lgkmcnt(2)
	v_mfma_f32_16x16x32_bf16 v[32:35], v[240:243], v[228:231], v[32:35]
	v_mfma_f32_16x16x32_bf16 v[36:39], v[244:247], v[228:231], v[36:39]
	v_mfma_f32_16x16x32_bf16 v[40:43], v[248:251], v[228:231], v[40:43]
	v_mfma_f32_16x16x32_bf16 v[44:47], v[252:255], v[228:231], v[44:47]
	s_waitcnt lgkmcnt(1)
	v_mfma_f32_16x16x32_bf16 v[48:51], v[240:243], v[232:235], v[48:51]
	v_mfma_f32_16x16x32_bf16 v[52:55], v[244:247], v[232:235], v[52:55]
	v_mfma_f32_16x16x32_bf16 v[56:59], v[248:251], v[232:235], v[56:59]
	v_mfma_f32_16x16x32_bf16 v[60:63], v[252:255], v[232:235], v[60:63]
	s_add_u32 s24, s24, 0x80
	s_addc_u32 s25, s25, 0
	s_waitcnt lgkmcnt(0)
	v_mfma_f32_16x16x32_bf16 v[64:67], v[240:243], v[236:239], v[64:67]
	v_mfma_f32_16x16x32_bf16 v[68:71], v[244:247], v[236:239], v[68:71]
	v_mfma_f32_16x16x32_bf16 v[72:75], v[248:251], v[236:239], v[72:75]
	v_mfma_f32_16x16x32_bf16 v[76:79], v[252:255], v[236:239], v[76:79]
	s_waitcnt vmcnt(0)
	s_barrier
	ds_read_b128 v[184:187], v116 offset:0
	ds_read_b128 v[204:207], v119 offset:36864
	ds_read_b128 v[208:211], v119 offset:38912
	ds_read_b128 v[212:215], v119 offset:40960
	ds_read_b128 v[216:219], v119 offset:43008
	ds_read_b128 v[188:191], v116 offset:2048
	ds_read_b128 v[192:195], v116 offset:4096
	ds_read_b128 v[196:199], v116 offset:6144
	ds_read_b128 v[200:203], v116 offset:8192
	s_waitcnt lgkmcnt(7)
	v_mfma_f32_16x16x32_bf16 v[80:83], v[204:207], v[184:187], v[80:83]
	s_add_u32 m0, s13, 0xd100
	s_nop 0
	global_load_lds_dwordx4 v161, s[2:3]
	s_waitcnt lgkmcnt(6)
	v_mfma_f32_16x16x32_bf16 v[84:87], v[208:211], v[184:187], v[84:87]
	s_add_u32 m0, s13, 0xe100
	v_add_u32_e32 v166, 0x10000, v161
	global_load_lds_dwordx4 v166, s[2:3]
	s_waitcnt lgkmcnt(5)
	v_mfma_f32_16x16x32_bf16 v[88:91], v[212:215], v[184:187], v[88:91]
	s_add_u32 m0, s13, 0xf100
	v_add_u32_e32 v166, 0x20000, v161
	global_load_lds_dwordx4 v166, s[2:3]
	s_waitcnt lgkmcnt(4)
	v_mfma_f32_16x16x32_bf16 v[92:95], v[216:219], v[184:187], v[92:95]
	s_add_u32 m0, s13, 0x10100
	v_add_u32_e32 v166, 0x30000, v161
	global_load_lds_dwordx4 v166, s[2:3]
	ds_read_b128 v[220:223], v118 offset:0
	ds_read_b128 v[240:243], v160 offset:36864
	ds_read_b128 v[244:247], v160 offset:38912
	ds_read_b128 v[248:251], v160 offset:40960
	ds_read_b128 v[252:255], v160 offset:43008
	s_waitcnt lgkmcnt(8)
	v_mfma_f32_16x16x32_bf16 v[96:99], v[204:207], v[188:191], v[96:99]
	s_add_u32 m0, s13, 0x11100
	v_add_u32_e32 v166, 0x40000, v161
	global_load_lds_dwordx4 v166, s[2:3]
	v_mfma_f32_16x16x32_bf16 v[100:103], v[208:211], v[188:191], v[100:103]
	s_add_u32 m0, s13, 0x5000
	s_nop 0
	global_load_lds_dwordx4 v165, s[6:7]
	v_mfma_f32_16x16x32_bf16 v[104:107], v[212:215], v[188:191], v[104:107]
	s_add_u32 m0, s13, 0x6000
	v_add_u32_e32 v166, 0x2000, v165
	global_load_lds_dwordx4 v166, s[6:7]
	v_mfma_f32_16x16x32_bf16 v[108:111], v[216:219], v[188:191], v[108:111]
	s_add_u32 m0, s13, 0x7000
	v_add_u32_e32 v166, 0x10000, v165
	global_load_lds_dwordx4 v166, s[6:7]
	ds_read_b128 v[224:227], v118 offset:2048
	ds_read_b128 v[228:231], v118 offset:4096
	ds_read_b128 v[232:235], v118 offset:6144
	ds_read_b128 v[236:239], v118 offset:8192
	s_waitcnt lgkmcnt(11)
	v_mfma_f32_16x16x32_bf16 v[112:115], v[204:207], v[192:195], v[112:115]
	s_add_u32 m0, s13, 0x8000
	v_add_u32_e32 v166, 0x12000, v165
	global_load_lds_dwordx4 v166, s[6:7]
	v_mfma_f32_16x16x32_bf16 v[120:123], v[208:211], v[192:195], v[120:123]
	v_mfma_f32_16x16x32_bf16 v[124:127], v[212:215], v[192:195], v[124:127]
	v_mfma_f32_16x16x32_bf16 v[140:143], v[216:219], v[192:195], v[140:143]
	s_waitcnt lgkmcnt(10)
	v_mfma_f32_16x16x32_bf16 v[144:147], v[204:207], v[196:199], v[144:147]
	v_mfma_f32_16x16x32_bf16 v[148:151], v[208:211], v[196:199], v[148:151]
	v_mfma_f32_16x16x32_bf16 v[152:155], v[212:215], v[196:199], v[152:155]
	v_mfma_f32_16x16x32_bf16 v[156:159], v[216:219], v[196:199], v[156:159]
	s_waitcnt lgkmcnt(9)
	v_mfma_f32_16x16x32_bf16 v[168:171], v[204:207], v[200:203], v[168:171]
	v_mfma_f32_16x16x32_bf16 v[172:175], v[208:211], v[200:203], v[172:175]
	v_mfma_f32_16x16x32_bf16 v[176:179], v[212:215], v[200:203], v[176:179]
	v_mfma_f32_16x16x32_bf16 v[180:183], v[216:219], v[200:203], v[180:183]
	s_waitcnt lgkmcnt(7)
	v_mfma_f32_16x16x32_bf16 v[80:83], v[240:243], v[220:223], v[80:83]
	s_waitcnt lgkmcnt(6)
	v_mfma_f32_16x16x32_bf16 v[84:87], v[244:247], v[220:223], v[84:87]
	s_waitcnt lgkmcnt(5)
	v_mfma_f32_16x16x32_bf16 v[88:91], v[248:251], v[220:223], v[88:91]
	s_waitcnt lgkmcnt(4)
	v_mfma_f32_16x16x32_bf16 v[92:95], v[252:255], v[220:223], v[92:95]
	s_waitcnt lgkmcnt(3)
	v_mfma_f32_16x16x32_bf16 v[96:99], v[240:243], v[224:227], v[96:99]
	v_mfma_f32_16x16x32_bf16 v[100:103], v[244:247], v[224:227], v[100:103]
	v_mfma_f32_16x16x32_bf16 v[104:107], v[248:251], v[224:227], v[104:107]
	v_mfma_f32_16x16x32_bf16 v[108:111], v[252:255], v[224:227], v[108:111]
	s_waitcnt lgkmcnt(2)
	v_mfma_f32_16x16x32_bf16 v[112:115], v[240:243], v[228:231], v[112:115]
	v_mfma_f32_16x16x32_bf16 v[120:123], v[244:247], v[228:231], v[120:123]
	v_mfma_f32_16x16x32_bf16 v[124:127], v[248:251], v[228:231], v[124:127]
	v_mfma_f32_16x16x32_bf16 v[140:143], v[252:255], v[228:231], v[140:143]
	s_waitcnt lgkmcnt(1)
	v_mfma_f32_16x16x32_bf16 v[144:147], v[240:243], v[232:235], v[144:147]
	v_mfma_f32_16x16x32_bf16 v[148:151], v[244:247], v[232:235], v[148:151]
	v_mfma_f32_16x16x32_bf16 v[152:155], v[248:251], v[232:235], v[152:155]
	v_mfma_f32_16x16x32_bf16 v[156:159], v[252:255], v[232:235], v[156:159]
	s_add_u32 s2, s2, 0x80
	s_addc_u32 s3, s3, 0
	s_add_u32 s6, s6, 0x80
	s_addc_u32 s7, s7, 0
	s_waitcnt lgkmcnt(0)
	v_mfma_f32_16x16x32_bf16 v[168:171], v[240:243], v[236:239], v[168:171]
	v_mfma_f32_16x16x32_bf16 v[172:175], v[244:247], v[236:239], v[172:175]
	v_mfma_f32_16x16x32_bf16 v[176:179], v[248:251], v[236:239], v[176:179]
	v_mfma_f32_16x16x32_bf16 v[180:183], v[252:255], v[236:239], v[180:183]
	s_waitcnt vmcnt(0)
	s_barrier
	ds_read_b128 v[184:187], v116 offset:53504
	ds_read_b128 v[204:207], v119 offset:20480
	ds_read_b128 v[208:211], v119 offset:22528
	ds_read_b128 v[212:215], v119 offset:24576
	ds_read_b128 v[216:219], v119 offset:26624
	ds_read_b128 v[188:191], v116 offset:55552
	ds_read_b128 v[192:195], v116 offset:57600
	ds_read_b128 v[196:199], v116 offset:59648
	ds_read_b128 v[200:203], v116 offset:61696
	s_waitcnt lgkmcnt(7)
	v_mfma_f32_16x16x32_bf16 v[0:3], v[204:207], v[184:187], v[0:3]
	s_add_u32 m0, s13, 0x9000
	s_nop 0
	global_load_lds_dwordx4 v165, s[24:25]
	s_waitcnt lgkmcnt(6)
	v_mfma_f32_16x16x32_bf16 v[4:7], v[208:211], v[184:187], v[4:7]
	s_add_u32 m0, s13, 0xa000
	v_add_u32_e32 v166, 0x2000, v165
	global_load_lds_dwordx4 v166, s[24:25]
	s_waitcnt lgkmcnt(5)
	v_mfma_f32_16x16x32_bf16 v[8:11], v[212:215], v[184:187], v[8:11]
	s_add_u32 m0, s13, 0xb000
	v_add_u32_e32 v166, 0x10000, v165
	global_load_lds_dwordx4 v166, s[24:25]
	s_waitcnt lgkmcnt(4)
	v_mfma_f32_16x16x32_bf16 v[12:15], v[216:219], v[184:187], v[12:15]
	s_add_u32 m0, s13, 0xc000
	v_add_u32_e32 v166, 0x12000, v165
	global_load_lds_dwordx4 v166, s[24:25]
	ds_read_b128 v[220:223], v118 offset:53504
	ds_read_b128 v[240:243], v160 offset:20480
	ds_read_b128 v[244:247], v160 offset:22528
	ds_read_b128 v[248:251], v160 offset:24576
	ds_read_b128 v[252:255], v160 offset:26624
	s_waitcnt lgkmcnt(8)
	v_mfma_f32_16x16x32_bf16 v[16:19], v[204:207], v[188:191], v[16:19]
	v_mfma_f32_16x16x32_bf16 v[20:23], v[208:211], v[188:191], v[20:23]
	v_mfma_f32_16x16x32_bf16 v[24:27], v[212:215], v[188:191], v[24:27]
	v_mfma_f32_16x16x32_bf16 v[28:31], v[216:219], v[188:191], v[28:31]
	ds_read_b128 v[224:227], v118 offset:55552
	ds_read_b128 v[228:231], v118 offset:57600
	ds_read_b128 v[232:235], v118 offset:59648
	ds_read_b128 v[236:239], v118 offset:61696
	s_waitcnt lgkmcnt(11)
	v_mfma_f32_16x16x32_bf16 v[32:35], v[204:207], v[192:195], v[32:35]
	v_mfma_f32_16x16x32_bf16 v[36:39], v[208:211], v[192:195], v[36:39]
	v_mfma_f32_16x16x32_bf16 v[40:43], v[212:215], v[192:195], v[40:43]
	v_mfma_f32_16x16x32_bf16 v[44:47], v[216:219], v[192:195], v[44:47]
	s_waitcnt lgkmcnt(10)
	v_mfma_f32_16x16x32_bf16 v[48:51], v[204:207], v[196:199], v[48:51]
	v_mfma_f32_16x16x32_bf16 v[52:55], v[208:211], v[196:199], v[52:55]
	v_mfma_f32_16x16x32_bf16 v[56:59], v[212:215], v[196:199], v[56:59]
	v_mfma_f32_16x16x32_bf16 v[60:63], v[216:219], v[196:199], v[60:63]
	s_waitcnt lgkmcnt(9)
	v_mfma_f32_16x16x32_bf16 v[64:67], v[204:207], v[200:203], v[64:67]
	v_mfma_f32_16x16x32_bf16 v[68:71], v[208:211], v[200:203], v[68:71]
	v_mfma_f32_16x16x32_bf16 v[72:75], v[212:215], v[200:203], v[72:75]
	v_mfma_f32_16x16x32_bf16 v[76:79], v[216:219], v[200:203], v[76:79]
	s_waitcnt lgkmcnt(7)
	v_mfma_f32_16x16x32_bf16 v[0:3], v[240:243], v[220:223], v[0:3]
	s_waitcnt lgkmcnt(6)
	v_mfma_f32_16x16x32_bf16 v[4:7], v[244:247], v[220:223], v[4:7]
	s_waitcnt lgkmcnt(5)
	v_mfma_f32_16x16x32_bf16 v[8:11], v[248:251], v[220:223], v[8:11]
	s_waitcnt lgkmcnt(4)
	v_mfma_f32_16x16x32_bf16 v[12:15], v[252:255], v[220:223], v[12:15]
	s_waitcnt lgkmcnt(3)
	v_mfma_f32_16x16x32_bf16 v[16:19], v[240:243], v[224:227], v[16:19]
	v_mfma_f32_16x16x32_bf16 v[20:23], v[244:247], v[224:227], v[20:23]
	v_mfma_f32_16x16x32_bf16 v[24:27], v[248:251], v[224:227], v[24:27]
	v_mfma_f32_16x16x32_bf16 v[28:31], v[252:255], v[224:227], v[28:31]
	s_waitcnt lgkmcnt(2)
	v_mfma_f32_16x16x32_bf16 v[32:35], v[240:243], v[228:231], v[32:35]
	v_mfma_f32_16x16x32_bf16 v[36:39], v[244:247], v[228:231], v[36:39]
	v_mfma_f32_16x16x32_bf16 v[40:43], v[248:251], v[228:231], v[40:43]
	v_mfma_f32_16x16x32_bf16 v[44:47], v[252:255], v[228:231], v[44:47]
	s_waitcnt lgkmcnt(1)
	v_mfma_f32_16x16x32_bf16 v[48:51], v[240:243], v[232:235], v[48:51]
	v_mfma_f32_16x16x32_bf16 v[52:55], v[244:247], v[232:235], v[52:55]
	v_mfma_f32_16x16x32_bf16 v[56:59], v[248:251], v[232:235], v[56:59]
	v_mfma_f32_16x16x32_bf16 v[60:63], v[252:255], v[232:235], v[60:63]
	s_add_u32 s24, s24, 0x80
	s_addc_u32 s25, s25, 0
	s_waitcnt lgkmcnt(0)
	v_mfma_f32_16x16x32_bf16 v[64:67], v[240:243], v[236:239], v[64:67]
	v_mfma_f32_16x16x32_bf16 v[68:71], v[244:247], v[236:239], v[68:71]
	v_mfma_f32_16x16x32_bf16 v[72:75], v[248:251], v[236:239], v[72:75]
	v_mfma_f32_16x16x32_bf16 v[76:79], v[252:255], v[236:239], v[76:79]
	s_cmp_eq_u32 s12, 1
	s_cselect_b32 s2, s20, s2
	s_cselect_b32 s3, s21, s3
	s_cselect_b32 s6, s22, s6
	s_cselect_b32 s7, s23, s7
	s_add_u32 s4, s22, 0x20000
	s_addc_u32 s32, s23, 0
	s_cmp_eq_u32 s12, 1
	s_cselect_b32 s24, s4, s24
	s_cselect_b32 s25, s32, s25
	s_waitcnt vmcnt(0)
	s_barrier
	ds_read_b128 v[184:187], v116 offset:53504
	ds_read_b128 v[204:207], v119 offset:36864
	ds_read_b128 v[208:211], v119 offset:38912
	ds_read_b128 v[212:215], v119 offset:40960
	ds_read_b128 v[216:219], v119 offset:43008
	ds_read_b128 v[188:191], v116 offset:55552
	ds_read_b128 v[192:195], v116 offset:57600
	ds_read_b128 v[196:199], v116 offset:59648
	ds_read_b128 v[200:203], v116 offset:61696
	s_waitcnt lgkmcnt(7)
	v_mfma_f32_16x16x32_bf16 v[80:83], v[204:207], v[184:187], v[80:83]
	s_add_u32 m0, s13, 0x0
	s_nop 0
	global_load_lds_dwordx4 v161, s[2:3]
	s_waitcnt lgkmcnt(6)
	v_mfma_f32_16x16x32_bf16 v[84:87], v[208:211], v[184:187], v[84:87]
	s_add_u32 m0, s13, 0x1000
	v_add_u32_e32 v166, 0x10000, v161
	global_load_lds_dwordx4 v166, s[2:3]
	s_waitcnt lgkmcnt(5)
	v_mfma_f32_16x16x32_bf16 v[88:91], v[212:215], v[184:187], v[88:91]
	s_add_u32 m0, s13, 0x2000
	v_add_u32_e32 v166, 0x20000, v161
	global_load_lds_dwordx4 v166, s[2:3]
	s_waitcnt lgkmcnt(4)
	v_mfma_f32_16x16x32_bf16 v[92:95], v[216:219], v[184:187], v[92:95]
	s_add_u32 m0, s13, 0x3000
	v_add_u32_e32 v166, 0x30000, v161
	global_load_lds_dwordx4 v166, s[2:3]
	ds_read_b128 v[220:223], v118 offset:53504
	ds_read_b128 v[240:243], v160 offset:36864
	ds_read_b128 v[244:247], v160 offset:38912
	ds_read_b128 v[248:251], v160 offset:40960
	ds_read_b128 v[252:255], v160 offset:43008
	s_waitcnt lgkmcnt(8)
	v_mfma_f32_16x16x32_bf16 v[96:99], v[204:207], v[188:191], v[96:99]
	s_add_u32 m0, s13, 0x4000
	v_add_u32_e32 v166, 0x40000, v161
	global_load_lds_dwordx4 v166, s[2:3]
	v_mfma_f32_16x16x32_bf16 v[100:103], v[208:211], v[188:191], v[100:103]
	s_add_u32 m0, s13, 0x5000
	s_nop 0
	global_load_lds_dwordx4 v165, s[6:7]
	v_mfma_f32_16x16x32_bf16 v[104:107], v[212:215], v[188:191], v[104:107]
	s_add_u32 m0, s13, 0x6000
	v_add_u32_e32 v166, 0x2000, v165
	global_load_lds_dwordx4 v166, s[6:7]
	v_mfma_f32_16x16x32_bf16 v[108:111], v[216:219], v[188:191], v[108:111]
	s_add_u32 m0, s13, 0x7000
	v_add_u32_e32 v166, 0x10000, v165
	global_load_lds_dwordx4 v166, s[6:7]
	ds_read_b128 v[224:227], v118 offset:55552
	ds_read_b128 v[228:231], v118 offset:57600
	ds_read_b128 v[232:235], v118 offset:59648
	ds_read_b128 v[236:239], v118 offset:61696
	s_waitcnt lgkmcnt(11)
	v_mfma_f32_16x16x32_bf16 v[112:115], v[204:207], v[192:195], v[112:115]
	s_add_u32 m0, s13, 0x8000
	v_add_u32_e32 v166, 0x12000, v165
	global_load_lds_dwordx4 v166, s[6:7]
	v_mfma_f32_16x16x32_bf16 v[120:123], v[208:211], v[192:195], v[120:123]
	v_mfma_f32_16x16x32_bf16 v[124:127], v[212:215], v[192:195], v[124:127]
	v_mfma_f32_16x16x32_bf16 v[140:143], v[216:219], v[192:195], v[140:143]
	s_waitcnt lgkmcnt(10)
	v_mfma_f32_16x16x32_bf16 v[144:147], v[204:207], v[196:199], v[144:147]
	v_mfma_f32_16x16x32_bf16 v[148:151], v[208:211], v[196:199], v[148:151]
	v_mfma_f32_16x16x32_bf16 v[152:155], v[212:215], v[196:199], v[152:155]
	v_mfma_f32_16x16x32_bf16 v[156:159], v[216:219], v[196:199], v[156:159]
	s_waitcnt lgkmcnt(9)
	v_mfma_f32_16x16x32_bf16 v[168:171], v[204:207], v[200:203], v[168:171]
	v_mfma_f32_16x16x32_bf16 v[172:175], v[208:211], v[200:203], v[172:175]
	v_mfma_f32_16x16x32_bf16 v[176:179], v[212:215], v[200:203], v[176:179]
	v_mfma_f32_16x16x32_bf16 v[180:183], v[216:219], v[200:203], v[180:183]
	s_waitcnt lgkmcnt(7)
	v_mfma_f32_16x16x32_bf16 v[80:83], v[240:243], v[220:223], v[80:83]
	s_waitcnt lgkmcnt(6)
	v_mfma_f32_16x16x32_bf16 v[84:87], v[244:247], v[220:223], v[84:87]
	s_waitcnt lgkmcnt(5)
	v_mfma_f32_16x16x32_bf16 v[88:91], v[248:251], v[220:223], v[88:91]
	s_waitcnt lgkmcnt(4)
	v_mfma_f32_16x16x32_bf16 v[92:95], v[252:255], v[220:223], v[92:95]
	s_waitcnt lgkmcnt(3)
	v_mfma_f32_16x16x32_bf16 v[96:99], v[240:243], v[224:227], v[96:99]
	v_mfma_f32_16x16x32_bf16 v[100:103], v[244:247], v[224:227], v[100:103]
	v_mfma_f32_16x16x32_bf16 v[104:107], v[248:251], v[224:227], v[104:107]
	v_mfma_f32_16x16x32_bf16 v[108:111], v[252:255], v[224:227], v[108:111]
	s_waitcnt lgkmcnt(2)
	v_mfma_f32_16x16x32_bf16 v[112:115], v[240:243], v[228:231], v[112:115]
	v_mfma_f32_16x16x32_bf16 v[120:123], v[244:247], v[228:231], v[120:123]
	v_mfma_f32_16x16x32_bf16 v[124:127], v[248:251], v[228:231], v[124:127]
	v_mfma_f32_16x16x32_bf16 v[140:143], v[252:255], v[228:231], v[140:143]
	s_waitcnt lgkmcnt(1)
	v_mfma_f32_16x16x32_bf16 v[144:147], v[240:243], v[232:235], v[144:147]
	v_mfma_f32_16x16x32_bf16 v[148:151], v[244:247], v[232:235], v[148:151]
	v_mfma_f32_16x16x32_bf16 v[152:155], v[248:251], v[232:235], v[152:155]
	v_mfma_f32_16x16x32_bf16 v[156:159], v[252:255], v[232:235], v[156:159]
	s_add_u32 s2, s2, 0x80
	s_addc_u32 s3, s3, 0
	s_add_u32 s6, s6, 0x80
	s_addc_u32 s7, s7, 0
	s_waitcnt lgkmcnt(0)
	v_mfma_f32_16x16x32_bf16 v[168:171], v[240:243], v[236:239], v[168:171]
	v_mfma_f32_16x16x32_bf16 v[172:175], v[244:247], v[236:239], v[172:175]
	v_mfma_f32_16x16x32_bf16 v[176:179], v[248:251], v[236:239], v[176:179]
	v_mfma_f32_16x16x32_bf16 v[180:183], v[252:255], v[236:239], v[180:183]
	s_sub_u32 s12, s12, 1
	s_cmp_lg_u32 s12, 0
	s_cbranch_scc1 .Lggu0_pair
	s_and_b32 s4, s10, 7
	s_lshl_b32 s4, s4, 3
	s_bfe_u32 s14, s10, 0x30003
	s_or_b32 s14, s14, s4
	s_lshr_b32 s15, s10, 6
	s_mul_i32 s4, s14, 0xdc000
	s_lshl_b32 s32, s15, 8
	s_add_u32 s4, s4, s32
	s_add_u32 s8, s76, s4
	s_addc_u32 s9, s77, 0
	s_mov_b32 s44, s8
	s_mov_b32 s46, s9
	s_nop 7
	v_mul_f32_e32 v184, 0xbfb8aa3b, v0
	v_mul_f32_e32 v185, 0xbfb8aa3b, v1
	v_mul_f32_e32 v186, 0xbfb8aa3b, v2
	v_mul_f32_e32 v187, 0xbfb8aa3b, v3
	v_exp_f32_e32 v184, v184
	v_exp_f32_e32 v185, v185
	v_exp_f32_e32 v186, v186
	v_exp_f32_e32 v187, v187
	s_nop 0
	v_add_f32_e32 v184, 1.0, v184
	v_add_f32_e32 v185, 1.0, v185
	v_add_f32_e32 v186, 1.0, v186
	v_add_f32_e32 v187, 1.0, v187
	v_rcp_f32_e32 v184, v184
	v_rcp_f32_e32 v185, v185
	v_rcp_f32_e32 v186, v186
	v_rcp_f32_e32 v187, v187
	s_nop 0
	v_mul_f32_e32 v184, v0, v184
	v_mul_f32_e32 v185, v1, v185
	v_mul_f32_e32 v186, v2, v186
	v_mul_f32_e32 v187, v3, v187
	v_mul_f32_e32 v184, v4, v184
	v_mul_f32_e32 v185, v5, v185
	v_mul_f32_e32 v186, v6, v186
	v_mul_f32_e32 v187, v7, v187
	v_mul_f32_e32 v192, 0xbfb8aa3b, v8
	v_mul_f32_e32 v193, 0xbfb8aa3b, v9
	v_mul_f32_e32 v194, 0xbfb8aa3b, v10
	v_mul_f32_e32 v195, 0xbfb8aa3b, v11
	v_exp_f32_e32 v192, v192
	v_exp_f32_e32 v193, v193
	v_exp_f32_e32 v194, v194
	v_exp_f32_e32 v195, v195
	s_nop 0
	v_add_f32_e32 v192, 1.0, v192
	v_add_f32_e32 v193, 1.0, v193
	v_add_f32_e32 v194, 1.0, v194
	v_add_f32_e32 v195, 1.0, v195
	v_rcp_f32_e32 v192, v192
	v_rcp_f32_e32 v193, v193
	v_rcp_f32_e32 v194, v194
	v_rcp_f32_e32 v195, v195
	s_nop 0
	v_mul_f32_e32 v192, v8, v192
	v_mul_f32_e32 v193, v9, v193
	v_mul_f32_e32 v194, v10, v194
	v_mul_f32_e32 v195, v11, v195
	v_mul_f32_e32 v192, v12, v192
	v_mul_f32_e32 v193, v13, v193
	v_mul_f32_e32 v194, v14, v194
	v_mul_f32_e32 v195, v15, v195
	v_cvt_pk_bf16_f32 v200, v184, v185
	v_cvt_pk_bf16_f32 v201, v186, v187
	v_cvt_pk_bf16_f32 v202, v192, v193
	v_cvt_pk_bf16_f32 v203, v194, v195
	global_store_dwordx4 v167, v[200:203], s[8:9]
	s_add_u32 s8, s8, 0x16000
	s_addc_u32 s9, s9, 0
	v_mul_f32_e32 v184, 0xbfb8aa3b, v16
	v_mul_f32_e32 v185, 0xbfb8aa3b, v17
	v_mul_f32_e32 v186, 0xbfb8aa3b, v18
	v_mul_f32_e32 v187, 0xbfb8aa3b, v19
	v_exp_f32_e32 v184, v184
	v_exp_f32_e32 v185, v185
	v_exp_f32_e32 v186, v186
	v_exp_f32_e32 v187, v187
	s_nop 0
	v_add_f32_e32 v184, 1.0, v184
	v_add_f32_e32 v185, 1.0, v185
	v_add_f32_e32 v186, 1.0, v186
	v_add_f32_e32 v187, 1.0, v187
	v_rcp_f32_e32 v184, v184
	v_rcp_f32_e32 v185, v185
	v_rcp_f32_e32 v186, v186
	v_rcp_f32_e32 v187, v187
	s_nop 0
	v_mul_f32_e32 v184, v16, v184
	v_mul_f32_e32 v185, v17, v185
	v_mul_f32_e32 v186, v18, v186
	v_mul_f32_e32 v187, v19, v187
	v_mul_f32_e32 v184, v20, v184
	v_mul_f32_e32 v185, v21, v185
	v_mul_f32_e32 v186, v22, v186
	v_mul_f32_e32 v187, v23, v187
	v_mul_f32_e32 v192, 0xbfb8aa3b, v24
	v_mul_f32_e32 v193, 0xbfb8aa3b, v25
	v_mul_f32_e32 v194, 0xbfb8aa3b, v26
	v_mul_f32_e32 v195, 0xbfb8aa3b, v27
	v_exp_f32_e32 v192, v192
	v_exp_f32_e32 v193, v193
	v_exp_f32_e32 v194, v194
	v_exp_f32_e32 v195, v195
	s_nop 0
	v_add_f32_e32 v192, 1.0, v192
	v_add_f32_e32 v193, 1.0, v193
	v_add_f32_e32 v194, 1.0, v194
	v_add_f32_e32 v195, 1.0, v195
	v_rcp_f32_e32 v192, v192
	v_rcp_f32_e32 v193, v193
	v_rcp_f32_e32 v194, v194
	v_rcp_f32_e32 v195, v195
	s_nop 0
	v_mul_f32_e32 v192, v24, v192
	v_mul_f32_e32 v193, v25, v193
	v_mul_f32_e32 v194, v26, v194
	v_mul_f32_e32 v195, v27, v195
	v_mul_f32_e32 v192, v28, v192
	v_mul_f32_e32 v193, v29, v193
	v_mul_f32_e32 v194, v30, v194
	v_mul_f32_e32 v195, v31, v195
	v_cvt_pk_bf16_f32 v204, v184, v185
	v_cvt_pk_bf16_f32 v205, v186, v187
	v_cvt_pk_bf16_f32 v206, v192, v193
	v_cvt_pk_bf16_f32 v207, v194, v195
	global_store_dwordx4 v167, v[204:207], s[8:9]
	s_add_u32 s8, s8, 0x16000
	s_addc_u32 s9, s9, 0
	v_mul_f32_e32 v184, 0xbfb8aa3b, v32
	v_mul_f32_e32 v185, 0xbfb8aa3b, v33
	v_mul_f32_e32 v186, 0xbfb8aa3b, v34
	v_mul_f32_e32 v187, 0xbfb8aa3b, v35
	v_exp_f32_e32 v184, v184
	v_exp_f32_e32 v185, v185
	v_exp_f32_e32 v186, v186
	v_exp_f32_e32 v187, v187
	s_nop 0
	v_add_f32_e32 v184, 1.0, v184
	v_add_f32_e32 v185, 1.0, v185
	v_add_f32_e32 v186, 1.0, v186
	v_add_f32_e32 v187, 1.0, v187
	v_rcp_f32_e32 v184, v184
	v_rcp_f32_e32 v185, v185
	v_rcp_f32_e32 v186, v186
	v_rcp_f32_e32 v187, v187
	s_nop 0
	v_mul_f32_e32 v184, v32, v184
	v_mul_f32_e32 v185, v33, v185
	v_mul_f32_e32 v186, v34, v186
	v_mul_f32_e32 v187, v35, v187
	v_mul_f32_e32 v184, v36, v184
	v_mul_f32_e32 v185, v37, v185
	v_mul_f32_e32 v186, v38, v186
	v_mul_f32_e32 v187, v39, v187
	v_mul_f32_e32 v192, 0xbfb8aa3b, v40
	v_mul_f32_e32 v193, 0xbfb8aa3b, v41
	v_mul_f32_e32 v194, 0xbfb8aa3b, v42
	v_mul_f32_e32 v195, 0xbfb8aa3b, v43
	v_exp_f32_e32 v192, v192
	v_exp_f32_e32 v193, v193
	v_exp_f32_e32 v194, v194
	v_exp_f32_e32 v195, v195
	s_nop 0
	v_add_f32_e32 v192, 1.0, v192
	v_add_f32_e32 v193, 1.0, v193
	v_add_f32_e32 v194, 1.0, v194
	v_add_f32_e32 v195, 1.0, v195
	v_rcp_f32_e32 v192, v192
	v_rcp_f32_e32 v193, v193
	v_rcp_f32_e32 v194, v194
	v_rcp_f32_e32 v195, v195
	s_nop 0
	v_mul_f32_e32 v192, v40, v192
	v_mul_f32_e32 v193, v41, v193
	v_mul_f32_e32 v194, v42, v194
	v_mul_f32_e32 v195, v43, v195
	v_mul_f32_e32 v192, v44, v192
	v_mul_f32_e32 v193, v45, v193
	v_mul_f32_e32 v194, v46, v194
	v_mul_f32_e32 v195, v47, v195
	v_cvt_pk_bf16_f32 v208, v184, v185
	v_cvt_pk_bf16_f32 v209, v186, v187
	v_cvt_pk_bf16_f32 v210, v192, v193
	v_cvt_pk_bf16_f32 v211, v194, v195
	global_store_dwordx4 v167, v[208:211], s[8:9]
	s_add_u32 s8, s8, 0x16000
	s_addc_u32 s9, s9, 0
	v_mul_f32_e32 v184, 0xbfb8aa3b, v48
	v_mul_f32_e32 v185, 0xbfb8aa3b, v49
	v_mul_f32_e32 v186, 0xbfb8aa3b, v50
	v_mul_f32_e32 v187, 0xbfb8aa3b, v51
	v_exp_f32_e32 v184, v184
	v_exp_f32_e32 v185, v185
	v_exp_f32_e32 v186, v186
	v_exp_f32_e32 v187, v187
	s_nop 0
	v_add_f32_e32 v184, 1.0, v184
	v_add_f32_e32 v185, 1.0, v185
	v_add_f32_e32 v186, 1.0, v186
	v_add_f32_e32 v187, 1.0, v187
	v_rcp_f32_e32 v184, v184
	v_rcp_f32_e32 v185, v185
	v_rcp_f32_e32 v186, v186
	v_rcp_f32_e32 v187, v187
	s_nop 0
	v_mul_f32_e32 v184, v48, v184
	v_mul_f32_e32 v185, v49, v185
	v_mul_f32_e32 v186, v50, v186
	v_mul_f32_e32 v187, v51, v187
	v_mul_f32_e32 v184, v52, v184
	v_mul_f32_e32 v185, v53, v185
	v_mul_f32_e32 v186, v54, v186
	v_mul_f32_e32 v187, v55, v187
	v_mul_f32_e32 v192, 0xbfb8aa3b, v56
	v_mul_f32_e32 v193, 0xbfb8aa3b, v57
	v_mul_f32_e32 v194, 0xbfb8aa3b, v58
	v_mul_f32_e32 v195, 0xbfb8aa3b, v59
	v_exp_f32_e32 v192, v192
	v_exp_f32_e32 v193, v193
	v_exp_f32_e32 v194, v194
	v_exp_f32_e32 v195, v195
	s_nop 0
	v_add_f32_e32 v192, 1.0, v192
	v_add_f32_e32 v193, 1.0, v193
	v_add_f32_e32 v194, 1.0, v194
	v_add_f32_e32 v195, 1.0, v195
	v_rcp_f32_e32 v192, v192
	v_rcp_f32_e32 v193, v193
	v_rcp_f32_e32 v194, v194
	v_rcp_f32_e32 v195, v195
	s_nop 0
	v_mul_f32_e32 v192, v56, v192
	v_mul_f32_e32 v193, v57, v193
	v_mul_f32_e32 v194, v58, v194
	v_mul_f32_e32 v195, v59, v195
	v_mul_f32_e32 v192, v60, v192
	v_mul_f32_e32 v193, v61, v193
	v_mul_f32_e32 v194, v62, v194
	v_mul_f32_e32 v195, v63, v195
	v_cvt_pk_bf16_f32 v212, v184, v185
	v_cvt_pk_bf16_f32 v213, v186, v187
	v_cvt_pk_bf16_f32 v214, v192, v193
	v_cvt_pk_bf16_f32 v215, v194, v195
	global_store_dwordx4 v167, v[212:215], s[8:9]
	s_add_u32 s8, s8, 0x16000
	s_addc_u32 s9, s9, 0
	v_mul_f32_e32 v184, 0xbfb8aa3b, v64
	v_mul_f32_e32 v185, 0xbfb8aa3b, v65
	v_mul_f32_e32 v186, 0xbfb8aa3b, v66
	v_mul_f32_e32 v187, 0xbfb8aa3b, v67
	v_exp_f32_e32 v184, v184
	v_exp_f32_e32 v185, v185
	v_exp_f32_e32 v186, v186
	v_exp_f32_e32 v187, v187
	s_nop 0
	v_add_f32_e32 v184, 1.0, v184
	v_add_f32_e32 v185, 1.0, v185
	v_add_f32_e32 v186, 1.0, v186
	v_add_f32_e32 v187, 1.0, v187
	v_rcp_f32_e32 v184, v184
	v_rcp_f32_e32 v185, v185
	v_rcp_f32_e32 v186, v186
	v_rcp_f32_e32 v187, v187
	s_nop 0
	v_mul_f32_e32 v184, v64, v184
	v_mul_f32_e32 v185, v65, v185
	v_mul_f32_e32 v186, v66, v186
	v_mul_f32_e32 v187, v67, v187
	v_mul_f32_e32 v184, v68, v184
	v_mul_f32_e32 v185, v69, v185
	v_mul_f32_e32 v186, v70, v186
	v_mul_f32_e32 v187, v71, v187
	v_mul_f32_e32 v192, 0xbfb8aa3b, v72
	v_mul_f32_e32 v193, 0xbfb8aa3b, v73
	v_mul_f32_e32 v194, 0xbfb8aa3b, v74
	v_mul_f32_e32 v195, 0xbfb8aa3b, v75
	v_exp_f32_e32 v192, v192
	v_exp_f32_e32 v193, v193
	v_exp_f32_e32 v194, v194
	v_exp_f32_e32 v195, v195
	s_nop 0
	v_add_f32_e32 v192, 1.0, v192
	v_add_f32_e32 v193, 1.0, v193
	v_add_f32_e32 v194, 1.0, v194
	v_add_f32_e32 v195, 1.0, v195
	v_rcp_f32_e32 v192, v192
	v_rcp_f32_e32 v193, v193
	v_rcp_f32_e32 v194, v194
	v_rcp_f32_e32 v195, v195
	s_nop 0
	v_mul_f32_e32 v192, v72, v192
	v_mul_f32_e32 v193, v73, v193
	v_mul_f32_e32 v194, v74, v194
	v_mul_f32_e32 v195, v75, v195
	v_mul_f32_e32 v192, v76, v192
	v_mul_f32_e32 v193, v77, v193
	v_mul_f32_e32 v194, v78, v194
	v_mul_f32_e32 v195, v79, v195
	v_cvt_pk_bf16_f32 v216, v184, v185
	v_cvt_pk_bf16_f32 v217, v186, v187
	v_cvt_pk_bf16_f32 v218, v192, v193
	v_cvt_pk_bf16_f32 v219, v194, v195
	global_store_dwordx4 v167, v[216:219], s[8:9]
	s_add_u32 s8, s44, 0x80
	s_addc_u32 s9, s46, 0
	v_mul_f32_e32 v184, 0xbfb8aa3b, v80
	v_mul_f32_e32 v185, 0xbfb8aa3b, v81
	v_mul_f32_e32 v186, 0xbfb8aa3b, v82
	v_mul_f32_e32 v187, 0xbfb8aa3b, v83
	v_exp_f32_e32 v184, v184
	v_exp_f32_e32 v185, v185
	v_exp_f32_e32 v186, v186
	v_exp_f32_e32 v187, v187
	s_nop 0
	v_add_f32_e32 v184, 1.0, v184
	v_add_f32_e32 v185, 1.0, v185
	v_add_f32_e32 v186, 1.0, v186
	v_add_f32_e32 v187, 1.0, v187
	v_rcp_f32_e32 v184, v184
	v_rcp_f32_e32 v185, v185
	v_rcp_f32_e32 v186, v186
	v_rcp_f32_e32 v187, v187
	s_nop 0
	v_mul_f32_e32 v184, v80, v184
	v_mul_f32_e32 v185, v81, v185
	v_mul_f32_e32 v186, v82, v186
	v_mul_f32_e32 v187, v83, v187
	v_mul_f32_e32 v184, v84, v184
	v_mul_f32_e32 v185, v85, v185
	v_mul_f32_e32 v186, v86, v186
	v_mul_f32_e32 v187, v87, v187
	v_mul_f32_e32 v192, 0xbfb8aa3b, v88
	v_mul_f32_e32 v193, 0xbfb8aa3b, v89
	v_mul_f32_e32 v194, 0xbfb8aa3b, v90
	v_mul_f32_e32 v195, 0xbfb8aa3b, v91
	v_exp_f32_e32 v192, v192
	v_exp_f32_e32 v193, v193
	v_exp_f32_e32 v194, v194
	v_exp_f32_e32 v195, v195
	s_nop 0
	v_add_f32_e32 v192, 1.0, v192
	v_add_f32_e32 v193, 1.0, v193
	v_add_f32_e32 v194, 1.0, v194
	v_add_f32_e32 v195, 1.0, v195
	v_rcp_f32_e32 v192, v192
	v_rcp_f32_e32 v193, v193
	v_rcp_f32_e32 v194, v194
	v_rcp_f32_e32 v195, v195
	s_nop 0
	v_mul_f32_e32 v192, v88, v192
	v_mul_f32_e32 v193, v89, v193
	v_mul_f32_e32 v194, v90, v194
	v_mul_f32_e32 v195, v91, v195
	v_mul_f32_e32 v192, v92, v192
	v_mul_f32_e32 v193, v93, v193
	v_mul_f32_e32 v194, v94, v194
	v_mul_f32_e32 v195, v95, v195
	v_cvt_pk_bf16_f32 v200, v184, v185
	v_cvt_pk_bf16_f32 v201, v186, v187
	v_cvt_pk_bf16_f32 v202, v192, v193
	v_cvt_pk_bf16_f32 v203, v194, v195
	global_store_dwordx4 v167, v[200:203], s[8:9]
	s_add_u32 s8, s8, 0x16000
	s_addc_u32 s9, s9, 0
	v_mul_f32_e32 v184, 0xbfb8aa3b, v96
	v_mul_f32_e32 v185, 0xbfb8aa3b, v97
	v_mul_f32_e32 v186, 0xbfb8aa3b, v98
	v_mul_f32_e32 v187, 0xbfb8aa3b, v99
	v_exp_f32_e32 v184, v184
	v_exp_f32_e32 v185, v185
	v_exp_f32_e32 v186, v186
	v_exp_f32_e32 v187, v187
	s_nop 0
	v_add_f32_e32 v184, 1.0, v184
	v_add_f32_e32 v185, 1.0, v185
	v_add_f32_e32 v186, 1.0, v186
	v_add_f32_e32 v187, 1.0, v187
	v_rcp_f32_e32 v184, v184
	v_rcp_f32_e32 v185, v185
	v_rcp_f32_e32 v186, v186
	v_rcp_f32_e32 v187, v187
	s_nop 0
	v_mul_f32_e32 v184, v96, v184
	v_mul_f32_e32 v185, v97, v185
	v_mul_f32_e32 v186, v98, v186
	v_mul_f32_e32 v187, v99, v187
	v_mul_f32_e32 v184, v100, v184
	v_mul_f32_e32 v185, v101, v185
	v_mul_f32_e32 v186, v102, v186
	v_mul_f32_e32 v187, v103, v187
	v_mul_f32_e32 v192, 0xbfb8aa3b, v104
	v_mul_f32_e32 v193, 0xbfb8aa3b, v105
	v_mul_f32_e32 v194, 0xbfb8aa3b, v106
	v_mul_f32_e32 v195, 0xbfb8aa3b, v107
	v_exp_f32_e32 v192, v192
	v_exp_f32_e32 v193, v193
	v_exp_f32_e32 v194, v194
	v_exp_f32_e32 v195, v195
	s_nop 0
	v_add_f32_e32 v192, 1.0, v192
	v_add_f32_e32 v193, 1.0, v193
	v_add_f32_e32 v194, 1.0, v194
	v_add_f32_e32 v195, 1.0, v195
	v_rcp_f32_e32 v192, v192
	v_rcp_f32_e32 v193, v193
	v_rcp_f32_e32 v194, v194
	v_rcp_f32_e32 v195, v195
	s_nop 0
	v_mul_f32_e32 v192, v104, v192
	v_mul_f32_e32 v193, v105, v193
	v_mul_f32_e32 v194, v106, v194
	v_mul_f32_e32 v195, v107, v195
	v_mul_f32_e32 v192, v108, v192
	v_mul_f32_e32 v193, v109, v193
	v_mul_f32_e32 v194, v110, v194
	v_mul_f32_e32 v195, v111, v195
	v_cvt_pk_bf16_f32 v204, v184, v185
	v_cvt_pk_bf16_f32 v205, v186, v187
	v_cvt_pk_bf16_f32 v206, v192, v193
	v_cvt_pk_bf16_f32 v207, v194, v195
	global_store_dwordx4 v167, v[204:207], s[8:9]
	s_add_u32 s8, s8, 0x16000
	s_addc_u32 s9, s9, 0
	v_mul_f32_e32 v184, 0xbfb8aa3b, v112
	v_mul_f32_e32 v185, 0xbfb8aa3b, v113
	v_mul_f32_e32 v186, 0xbfb8aa3b, v114
	v_mul_f32_e32 v187, 0xbfb8aa3b, v115
	v_exp_f32_e32 v184, v184
	v_exp_f32_e32 v185, v185
	v_exp_f32_e32 v186, v186
	v_exp_f32_e32 v187, v187
	s_nop 0
	v_add_f32_e32 v184, 1.0, v184
	v_add_f32_e32 v185, 1.0, v185
	v_add_f32_e32 v186, 1.0, v186
	v_add_f32_e32 v187, 1.0, v187
	v_rcp_f32_e32 v184, v184
	v_rcp_f32_e32 v185, v185
	v_rcp_f32_e32 v186, v186
	v_rcp_f32_e32 v187, v187
	s_nop 0
	v_mul_f32_e32 v184, v112, v184
	v_mul_f32_e32 v185, v113, v185
	v_mul_f32_e32 v186, v114, v186
	v_mul_f32_e32 v187, v115, v187
	v_mul_f32_e32 v184, v120, v184
	v_mul_f32_e32 v185, v121, v185
	v_mul_f32_e32 v186, v122, v186
	v_mul_f32_e32 v187, v123, v187
	v_mul_f32_e32 v192, 0xbfb8aa3b, v124
	v_mul_f32_e32 v193, 0xbfb8aa3b, v125
	v_mul_f32_e32 v194, 0xbfb8aa3b, v126
	v_mul_f32_e32 v195, 0xbfb8aa3b, v127
	v_exp_f32_e32 v192, v192
	v_exp_f32_e32 v193, v193
	v_exp_f32_e32 v194, v194
	v_exp_f32_e32 v195, v195
	s_nop 0
	v_add_f32_e32 v192, 1.0, v192
	v_add_f32_e32 v193, 1.0, v193
	v_add_f32_e32 v194, 1.0, v194
	v_add_f32_e32 v195, 1.0, v195
	v_rcp_f32_e32 v192, v192
	v_rcp_f32_e32 v193, v193
	v_rcp_f32_e32 v194, v194
	v_rcp_f32_e32 v195, v195
	s_nop 0
	v_mul_f32_e32 v192, v124, v192
	v_mul_f32_e32 v193, v125, v193
	v_mul_f32_e32 v194, v126, v194
	v_mul_f32_e32 v195, v127, v195
	v_mul_f32_e32 v192, v140, v192
	v_mul_f32_e32 v193, v141, v193
	v_mul_f32_e32 v194, v142, v194
	v_mul_f32_e32 v195, v143, v195
	v_cvt_pk_bf16_f32 v208, v184, v185
	v_cvt_pk_bf16_f32 v209, v186, v187
	v_cvt_pk_bf16_f32 v210, v192, v193
	v_cvt_pk_bf16_f32 v211, v194, v195
	global_store_dwordx4 v167, v[208:211], s[8:9]
	s_add_u32 s8, s8, 0x16000
	s_addc_u32 s9, s9, 0
	v_mul_f32_e32 v184, 0xbfb8aa3b, v144
	v_mul_f32_e32 v185, 0xbfb8aa3b, v145
	v_mul_f32_e32 v186, 0xbfb8aa3b, v146
	v_mul_f32_e32 v187, 0xbfb8aa3b, v147
	v_exp_f32_e32 v184, v184
	v_exp_f32_e32 v185, v185
	v_exp_f32_e32 v186, v186
	v_exp_f32_e32 v187, v187
	s_nop 0
	v_add_f32_e32 v184, 1.0, v184
	v_add_f32_e32 v185, 1.0, v185
	v_add_f32_e32 v186, 1.0, v186
	v_add_f32_e32 v187, 1.0, v187
	v_rcp_f32_e32 v184, v184
	v_rcp_f32_e32 v185, v185
	v_rcp_f32_e32 v186, v186
	v_rcp_f32_e32 v187, v187
	s_nop 0
	v_mul_f32_e32 v184, v144, v184
	v_mul_f32_e32 v185, v145, v185
	v_mul_f32_e32 v186, v146, v186
	v_mul_f32_e32 v187, v147, v187
	v_mul_f32_e32 v184, v148, v184
	v_mul_f32_e32 v185, v149, v185
	v_mul_f32_e32 v186, v150, v186
	v_mul_f32_e32 v187, v151, v187
	v_mul_f32_e32 v192, 0xbfb8aa3b, v152
	v_mul_f32_e32 v193, 0xbfb8aa3b, v153
	v_mul_f32_e32 v194, 0xbfb8aa3b, v154
	v_mul_f32_e32 v195, 0xbfb8aa3b, v155
	v_exp_f32_e32 v192, v192
	v_exp_f32_e32 v193, v193
	v_exp_f32_e32 v194, v194
	v_exp_f32_e32 v195, v195
	s_nop 0
	v_add_f32_e32 v192, 1.0, v192
	v_add_f32_e32 v193, 1.0, v193
	v_add_f32_e32 v194, 1.0, v194
	v_add_f32_e32 v195, 1.0, v195
	v_rcp_f32_e32 v192, v192
	v_rcp_f32_e32 v193, v193
	v_rcp_f32_e32 v194, v194
	v_rcp_f32_e32 v195, v195
	s_nop 0
	v_mul_f32_e32 v192, v152, v192
	v_mul_f32_e32 v193, v153, v193
	v_mul_f32_e32 v194, v154, v194
	v_mul_f32_e32 v195, v155, v195
	v_mul_f32_e32 v192, v156, v192
	v_mul_f32_e32 v193, v157, v193
	v_mul_f32_e32 v194, v158, v194
	v_mul_f32_e32 v195, v159, v195
	v_cvt_pk_bf16_f32 v212, v184, v185
	v_cvt_pk_bf16_f32 v213, v186, v187
	v_cvt_pk_bf16_f32 v214, v192, v193
	v_cvt_pk_bf16_f32 v215, v194, v195
	global_store_dwordx4 v167, v[212:215], s[8:9]
	s_add_u32 s8, s8, 0x16000
	s_addc_u32 s9, s9, 0
	v_mul_f32_e32 v184, 0xbfb8aa3b, v168
	v_mul_f32_e32 v185, 0xbfb8aa3b, v169
	v_mul_f32_e32 v186, 0xbfb8aa3b, v170
	v_mul_f32_e32 v187, 0xbfb8aa3b, v171
	v_exp_f32_e32 v184, v184
	v_exp_f32_e32 v185, v185
	v_exp_f32_e32 v186, v186
	v_exp_f32_e32 v187, v187
	s_nop 0
	v_add_f32_e32 v184, 1.0, v184
	v_add_f32_e32 v185, 1.0, v185
	v_add_f32_e32 v186, 1.0, v186
	v_add_f32_e32 v187, 1.0, v187
	v_rcp_f32_e32 v184, v184
	v_rcp_f32_e32 v185, v185
	v_rcp_f32_e32 v186, v186
	v_rcp_f32_e32 v187, v187
	s_nop 0
	v_mul_f32_e32 v184, v168, v184
	v_mul_f32_e32 v185, v169, v185
	v_mul_f32_e32 v186, v170, v186
	v_mul_f32_e32 v187, v171, v187
	v_mul_f32_e32 v184, v172, v184
	v_mul_f32_e32 v185, v173, v185
	v_mul_f32_e32 v186, v174, v186
	v_mul_f32_e32 v187, v175, v187
	v_mul_f32_e32 v192, 0xbfb8aa3b, v176
	v_mul_f32_e32 v193, 0xbfb8aa3b, v177
	v_mul_f32_e32 v194, 0xbfb8aa3b, v178
	v_mul_f32_e32 v195, 0xbfb8aa3b, v179
	v_exp_f32_e32 v192, v192
	v_exp_f32_e32 v193, v193
	v_exp_f32_e32 v194, v194
	v_exp_f32_e32 v195, v195
	s_nop 0
	v_add_f32_e32 v192, 1.0, v192
	v_add_f32_e32 v193, 1.0, v193
	v_add_f32_e32 v194, 1.0, v194
	v_add_f32_e32 v195, 1.0, v195
	v_rcp_f32_e32 v192, v192
	v_rcp_f32_e32 v193, v193
	v_rcp_f32_e32 v194, v194
	v_rcp_f32_e32 v195, v195
	s_nop 0
	v_mul_f32_e32 v192, v176, v192
	v_mul_f32_e32 v193, v177, v193
	v_mul_f32_e32 v194, v178, v194
	v_mul_f32_e32 v195, v179, v195
	v_mul_f32_e32 v192, v180, v192
	v_mul_f32_e32 v193, v181, v193
	v_mul_f32_e32 v194, v182, v194
	v_mul_f32_e32 v195, v183, v195
	v_cvt_pk_bf16_f32 v216, v184, v185
	v_cvt_pk_bf16_f32 v217, v186, v187
	v_cvt_pk_bf16_f32 v218, v192, v193
	v_cvt_pk_bf16_f32 v219, v194, v195
	global_store_dwordx4 v167, v[216:219], s[8:9]
	s_add_u32 s10, s10, s11
	s_cmp_lt_u32 s10, 0x580
	s_cbranch_scc1 .Lggu0_tile
.Lggu0_done:
	s_setprio 0
.LBB0_197:
	s_mul_i32 s2, s34, 12
	v_readlane_b32 s20, v162, 12
	s_or_b32 s35, s2, 3
	v_readlane_b32 s21, v162, 13
	s_cmp_ge_u32 s35, s21
	v_readlane_b32 s22, v162, 14
	v_readlane_b32 s23, v162, 15
	s_cbranch_scc1 .LBB0_247
	s_waitcnt vmcnt(0)
	v_readlane_b32 s4, v163, 17
	v_readlane_b32 s5, v163, 18
	s_barrier
	s_and_saveexec_b64 s[2:3], s[4:5]
	s_cbranch_execz .LBB0_246
	s_waitcnt vmcnt(0) expcnt(0) lgkmcnt(0)
	ds_read_b32 v2, v117 offset:53248
	ds_read_b32 v0, v117 offset:53252
	s_waitcnt lgkmcnt(1)
	v_cmp_ne_u32_e32 vcc, 0, v2
	s_cbranch_vccnz .LBB0_214
	s_mov_b32 s36, 1
	s_branch .LBB0_202

.LBB0_249:
	s_andn2_b64 vcc, exec, s[2:3]
	s_mul_i32 s2, s34, 0x580000
	v_writelane_b32 v162, s2, 39
	s_nop 1
	v_writelane_b32 v162, s3, 40
	s_nop 0
	v_readlane_b32 s2, v162, 6
	v_readlane_b32 s3, v162, 7
	s_nop 1
	v_cndmask_b32_e64 v0, 0, 1, s[2:3]
	v_cmp_ne_u32_e64 s[2:3], 1, v0
	s_nop 1
	v_writelane_b32 v162, s2, 41
	s_nop 1
	v_writelane_b32 v162, s3, 42
	s_cbranch_vccnz .LBB0_317
	v_readlane_b32 s10, v164, 0
	v_readlane_b32 s11, v162, 14
	s_mov_b32 s16, s76
	s_mov_b32 s17, s77
	v_readlane_b32 s18, v163, 7
	v_readlane_b32 s19, v163, 8
	s_mul_i32 s4, s34, 0xb00000
	s_add_u32 s18, s18, s4
	s_addc_u32 s19, s19, 0
	s_movk_i32 s42, 0x1600
	v_and_b32_e32 v220, 63, v128
	v_lshrrev_b32_e32 v221, 6, v128
	v_and_b32_e32 v222, 15, v220
	v_lshrrev_b32_e32 v223, 4, v220
	v_readfirstlane_b32 s40, v221
	v_bfe_u32 v224, v222, 1, 3
	s_lshl_b32 s13, s40, 10
	s_and_b32 s36, s40, 1
	s_lshr_b32 s35, s40, 1
	v_xor_b32_e32 v225, v223, v224
	v_lshlrev_b32_e32 v225, 4, v225
	s_mul_i32 s4, s35, 0x50
	v_add_u32_e32 v226, s4, v222
	v_lshl_add_u32 v204, v226, 7, v225
	v_xor_b32_e32 v205, 64, v204
	s_lshl_b32 s4, s36, 6
	v_add_u32_e32 v227, s4, v222
	v_lshl_add_u32 v206, v227, 7, v225
	v_xor_b32_e32 v207, 64, v206
	v_and_b32_e32 v228, 7, v220
	v_lshrrev_b32_e32 v229, 3, v220
	v_xor_b32_e32 v230, v228, v223
	s_lshl_b32 s4, s36, 2
	v_xor_b32_e32 v230, s4, v230
	v_lshlrev_b32_e32 v230, 4, v230
	s_lshl_b32 s4, s40, 3
	v_add_u32_e32 v231, s4, v229
	v_mad_u32_u24 v208, v231, s42, v230
	v_add_u32_e32 v209, 0x2c000, v208
	v_add_u32_e32 v210, 0x58000, v208
	v_add_u32_e32 v211, 0x84000, v208
	v_add_u32_e32 v212, 0xb0000, v208
	v_bfe_u32 v232, v231, 2, 2
	v_and_b32_e32 v233, 3, v231
	v_lshrrev_b32_e32 v234, 4, v231
	v_lshl_add_u32 v232, v232, 3, v233
	v_lshl_add_u32 v232, v234, 2, v232
	v_mad_u32_u24 v213, v232, s42, v230
	v_add_u32_e32 v214, 0x2c000, v213
	v_add_u32_e32 v215, 0x58000, v213
	v_add_u32_e32 v216, 0x84000, v213
	v_lshlrev_b32_e32 v217, 11, v226
	v_lshl_add_u32 v217, v223, 4, v217
	s_lshl_b32 s4, s36, 7
	v_add_u32_e32 v217, s4, v217
	s_cmp_ge_u32 s10, 0x200
	s_cbranch_scc1 .Lgdn0_done
	s_getreg_b32 s4, hwreg(HW_REG_HW_ID, 0, 4)
	s_and_b32 s4, s4, 1
	s_cmp_eq_u32 s4, 0
	s_cbranch_scc1 .Lgdn0_noprio
	s_setprio 1
.Lgdn0_noprio:
	s_and_b32 s4, s10, 7
	s_lshl_b32 s4, s4, 3
	s_bfe_u32 s32, s10, 0x30003
	s_or_b32 s4, s4, s32
	s_mul_i32 s4, s4, 0xdc000
	s_add_u32 s2, s16, s4
	s_addc_u32 s3, s17, 0
	s_lshr_b32 s4, s10, 6
	s_mul_i32 s4, s4, 0xb0000
	s_add_u32 s6, s18, s4
	s_addc_u32 s7, s19, 0
	s_add_u32 m0, s13, 0x0
	s_nop 0
	global_load_lds_dwordx4 v208, s[2:3]
	s_add_u32 m0, s13, 0x1000
	s_nop 0
	global_load_lds_dwordx4 v209, s[2:3]
	s_add_u32 m0, s13, 0x2000
	s_nop 0
	global_load_lds_dwordx4 v210, s[2:3]
	s_add_u32 m0, s13, 0x3000
	s_nop 0
	global_load_lds_dwordx4 v211, s[2:3]
	s_add_u32 m0, s13, 0x4000
	s_nop 0
	global_load_lds_dwordx4 v212, s[2:3]
	s_add_u32 m0, s13, 0x5000
	s_nop 0
	global_load_lds_dwordx4 v213, s[6:7]
	s_add_u32 m0, s13, 0x6000
	s_nop 0
	global_load_lds_dwordx4 v214, s[6:7]
	s_add_u32 m0, s13, 0x7000
	s_nop 0
	global_load_lds_dwordx4 v215, s[6:7]
	s_add_u32 m0, s13, 0x8000
	s_nop 0
	global_load_lds_dwordx4 v216, s[6:7]
	s_add_u32 s2, s2, 0x80
	s_addc_u32 s3, s3, 0
	s_add_u32 s6, s6, 0x80
	s_addc_u32 s7, s7, 0

.Lgdn0_pair:
	s_waitcnt vmcnt(0)
	s_barrier
	ds_read_b128 v[80:83], v204 offset:0
	ds_read_b128 v[100:103], v206 offset:20480
	ds_read_b128 v[104:107], v206 offset:22528
	ds_read_b128 v[108:111], v206 offset:24576
	ds_read_b128 v[112:115], v206 offset:26624
	ds_read_b128 v[84:87], v204 offset:2048
	ds_read_b128 v[88:91], v204 offset:4096
	ds_read_b128 v[92:95], v204 offset:6144
	ds_read_b128 v[96:99], v204 offset:8192
	s_add_u32 m0, s13, 0xd100
	s_waitcnt lgkmcnt(7)
	v_mfma_f32_16x16x32_bf16 v[0:3], v[100:103], v[80:83], v[0:3]
	global_load_lds_dwordx4 v208, s[2:3]
	s_add_u32 m0, s13, 0xe100
	s_waitcnt lgkmcnt(6)
	v_mfma_f32_16x16x32_bf16 v[4:7], v[104:107], v[80:83], v[4:7]
	global_load_lds_dwordx4 v209, s[2:3]
	s_add_u32 m0, s13, 0xf100
	s_waitcnt lgkmcnt(5)
	v_mfma_f32_16x16x32_bf16 v[8:11], v[108:111], v[80:83], v[8:11]
	global_load_lds_dwordx4 v210, s[2:3]
	s_add_u32 m0, s13, 0x10100
	s_waitcnt lgkmcnt(4)
	v_mfma_f32_16x16x32_bf16 v[12:15], v[112:115], v[80:83], v[12:15]
	global_load_lds_dwordx4 v211, s[2:3]
	s_add_u32 m0, s13, 0x11100
	ds_read_b128 v[168:171], v205 offset:0
	ds_read_b128 v[188:191], v207 offset:20480
	ds_read_b128 v[192:195], v207 offset:22528
	ds_read_b128 v[196:199], v207 offset:24576
	ds_read_b128 v[200:203], v207 offset:26624
	s_waitcnt lgkmcnt(8)
	v_mfma_f32_16x16x32_bf16 v[16:19], v[100:103], v[84:87], v[16:19]
	global_load_lds_dwordx4 v212, s[2:3]
	s_add_u32 m0, s13, 0x9000
	v_mfma_f32_16x16x32_bf16 v[20:23], v[104:107], v[84:87], v[20:23]
	global_load_lds_dwordx4 v213, s[6:7]
	s_add_u32 m0, s13, 0xa000
	v_mfma_f32_16x16x32_bf16 v[24:27], v[108:111], v[84:87], v[24:27]
	global_load_lds_dwordx4 v214, s[6:7]
	s_add_u32 m0, s13, 0xb000
	v_mfma_f32_16x16x32_bf16 v[28:31], v[112:115], v[84:87], v[28:31]
	global_load_lds_dwordx4 v215, s[6:7]
	s_add_u32 m0, s13, 0xc000
	ds_read_b128 v[172:175], v205 offset:2048
	ds_read_b128 v[176:179], v205 offset:4096
	ds_read_b128 v[180:183], v205 offset:6144
	ds_read_b128 v[184:187], v205 offset:8192
	s_waitcnt lgkmcnt(11)
	v_mfma_f32_16x16x32_bf16 v[32:35], v[100:103], v[88:91], v[32:35]
	global_load_lds_dwordx4 v216, s[6:7]
	v_mfma_f32_16x16x32_bf16 v[36:39], v[104:107], v[88:91], v[36:39]
	v_mfma_f32_16x16x32_bf16 v[40:43], v[108:111], v[88:91], v[40:43]
	v_mfma_f32_16x16x32_bf16 v[44:47], v[112:115], v[88:91], v[44:47]
	s_waitcnt lgkmcnt(10)
	v_mfma_f32_16x16x32_bf16 v[48:51], v[100:103], v[92:95], v[48:51]
	v_mfma_f32_16x16x32_bf16 v[52:55], v[104:107], v[92:95], v[52:55]
	v_mfma_f32_16x16x32_bf16 v[56:59], v[108:111], v[92:95], v[56:59]
	v_mfma_f32_16x16x32_bf16 v[60:63], v[112:115], v[92:95], v[60:63]
	s_waitcnt lgkmcnt(9)
	v_mfma_f32_16x16x32_bf16 v[64:67], v[100:103], v[96:99], v[64:67]
	v_mfma_f32_16x16x32_bf16 v[68:71], v[104:107], v[96:99], v[68:71]
	v_mfma_f32_16x16x32_bf16 v[72:75], v[108:111], v[96:99], v[72:75]
	v_mfma_f32_16x16x32_bf16 v[76:79], v[112:115], v[96:99], v[76:79]
	s_waitcnt lgkmcnt(7)
	v_mfma_f32_16x16x32_bf16 v[0:3], v[188:191], v[168:171], v[0:3]
	s_waitcnt lgkmcnt(6)
	v_mfma_f32_16x16x32_bf16 v[4:7], v[192:195], v[168:171], v[4:7]
	s_waitcnt lgkmcnt(5)
	v_mfma_f32_16x16x32_bf16 v[8:11], v[196:199], v[168:171], v[8:11]
	s_waitcnt lgkmcnt(4)
	v_mfma_f32_16x16x32_bf16 v[12:15], v[200:203], v[168:171], v[12:15]
	s_waitcnt lgkmcnt(3)
	v_mfma_f32_16x16x32_bf16 v[16:19], v[188:191], v[172:175], v[16:19]
	v_mfma_f32_16x16x32_bf16 v[20:23], v[192:195], v[172:175], v[20:23]
	v_mfma_f32_16x16x32_bf16 v[24:27], v[196:199], v[172:175], v[24:27]
	v_mfma_f32_16x16x32_bf16 v[28:31], v[200:203], v[172:175], v[28:31]
	s_waitcnt lgkmcnt(2)
	v_mfma_f32_16x16x32_bf16 v[32:35], v[188:191], v[176:179], v[32:35]
	v_mfma_f32_16x16x32_bf16 v[36:39], v[192:195], v[176:179], v[36:39]
	v_mfma_f32_16x16x32_bf16 v[40:43], v[196:199], v[176:179], v[40:43]
	v_mfma_f32_16x16x32_bf16 v[44:47], v[200:203], v[176:179], v[44:47]
	s_waitcnt lgkmcnt(1)
	v_mfma_f32_16x16x32_bf16 v[48:51], v[188:191], v[180:183], v[48:51]
	v_mfma_f32_16x16x32_bf16 v[52:55], v[192:195], v[180:183], v[52:55]
	v_mfma_f32_16x16x32_bf16 v[56:59], v[196:199], v[180:183], v[56:59]
	v_mfma_f32_16x16x32_bf16 v[60:63], v[200:203], v[180:183], v[60:63]
	s_add_u32 s2, s2, 0x80
	s_addc_u32 s3, s3, 0
	s_add_u32 s6, s6, 0x80
	s_addc_u32 s7, s7, 0
	s_waitcnt lgkmcnt(0)
	v_mfma_f32_16x16x32_bf16 v[64:67], v[188:191], v[184:187], v[64:67]
	v_mfma_f32_16x16x32_bf16 v[68:71], v[192:195], v[184:187], v[68:71]
	v_mfma_f32_16x16x32_bf16 v[72:75], v[196:199], v[184:187], v[72:75]
	v_mfma_f32_16x16x32_bf16 v[76:79], v[200:203], v[184:187], v[76:79]
	s_cmp_eq_u32 s12, 1
	s_cselect_b32 s2, s20, s2
	s_cselect_b32 s3, s21, s3
	s_cselect_b32 s6, s22, s6
	s_cselect_b32 s7, s23, s7
	s_waitcnt vmcnt(0)
	s_barrier
	ds_read_b128 v[80:83], v204 offset:53504
	ds_read_b128 v[100:103], v206 offset:36864
	ds_read_b128 v[104:107], v206 offset:38912
	ds_read_b128 v[108:111], v206 offset:40960
	ds_read_b128 v[112:115], v206 offset:43008
	ds_read_b128 v[84:87], v204 offset:55552
	ds_read_b128 v[88:91], v204 offset:57600
	ds_read_b128 v[92:95], v204 offset:59648
	ds_read_b128 v[96:99], v204 offset:61696
	s_add_u32 m0, s13, 0x0
	s_waitcnt lgkmcnt(7)
	v_mfma_f32_16x16x32_bf16 v[0:3], v[100:103], v[80:83], v[0:3]
	global_load_lds_dwordx4 v208, s[2:3]
	s_add_u32 m0, s13, 0x1000
	s_waitcnt lgkmcnt(6)
	v_mfma_f32_16x16x32_bf16 v[4:7], v[104:107], v[80:83], v[4:7]
	global_load_lds_dwordx4 v209, s[2:3]
	s_add_u32 m0, s13, 0x2000
	s_waitcnt lgkmcnt(5)
	v_mfma_f32_16x16x32_bf16 v[8:11], v[108:111], v[80:83], v[8:11]
	global_load_lds_dwordx4 v210, s[2:3]
	s_add_u32 m0, s13, 0x3000
	s_waitcnt lgkmcnt(4)
	v_mfma_f32_16x16x32_bf16 v[12:15], v[112:115], v[80:83], v[12:15]
	global_load_lds_dwordx4 v211, s[2:3]
	s_add_u32 m0, s13, 0x4000
	ds_read_b128 v[168:171], v205 offset:53504
	ds_read_b128 v[188:191], v207 offset:36864
	ds_read_b128 v[192:195], v207 offset:38912
	ds_read_b128 v[196:199], v207 offset:40960
	ds_read_b128 v[200:203], v207 offset:43008
	s_waitcnt lgkmcnt(8)
	v_mfma_f32_16x16x32_bf16 v[16:19], v[100:103], v[84:87], v[16:19]
	global_load_lds_dwordx4 v212, s[2:3]
	s_add_u32 m0, s13, 0x5000
	v_mfma_f32_16x16x32_bf16 v[20:23], v[104:107], v[84:87], v[20:23]
	global_load_lds_dwordx4 v213, s[6:7]
	s_add_u32 m0, s13, 0x6000
	v_mfma_f32_16x16x32_bf16 v[24:27], v[108:111], v[84:87], v[24:27]
	global_load_lds_dwordx4 v214, s[6:7]
	s_add_u32 m0, s13, 0x7000
	v_mfma_f32_16x16x32_bf16 v[28:31], v[112:115], v[84:87], v[28:31]
	global_load_lds_dwordx4 v215, s[6:7]
	s_add_u32 m0, s13, 0x8000
	ds_read_b128 v[172:175], v205 offset:55552
	ds_read_b128 v[176:179], v205 offset:57600
	ds_read_b128 v[180:183], v205 offset:59648
	ds_read_b128 v[184:187], v205 offset:61696
	s_waitcnt lgkmcnt(11)
	v_mfma_f32_16x16x32_bf16 v[32:35], v[100:103], v[88:91], v[32:35]
	global_load_lds_dwordx4 v216, s[6:7]
	v_mfma_f32_16x16x32_bf16 v[36:39], v[104:107], v[88:91], v[36:39]
	v_mfma_f32_16x16x32_bf16 v[40:43], v[108:111], v[88:91], v[40:43]
	v_mfma_f32_16x16x32_bf16 v[44:47], v[112:115], v[88:91], v[44:47]
	s_waitcnt lgkmcnt(10)
	v_mfma_f32_16x16x32_bf16 v[48:51], v[100:103], v[92:95], v[48:51]
	v_mfma_f32_16x16x32_bf16 v[52:55], v[104:107], v[92:95], v[52:55]
	v_mfma_f32_16x16x32_bf16 v[56:59], v[108:111], v[92:95], v[56:59]
	v_mfma_f32_16x16x32_bf16 v[60:63], v[112:115], v[92:95], v[60:63]
	s_waitcnt lgkmcnt(9)
	v_mfma_f32_16x16x32_bf16 v[64:67], v[100:103], v[96:99], v[64:67]
	v_mfma_f32_16x16x32_bf16 v[68:71], v[104:107], v[96:99], v[68:71]
	v_mfma_f32_16x16x32_bf16 v[72:75], v[108:111], v[96:99], v[72:75]
	v_mfma_f32_16x16x32_bf16 v[76:79], v[112:115], v[96:99], v[76:79]
	s_waitcnt lgkmcnt(7)
	v_mfma_f32_16x16x32_bf16 v[0:3], v[188:191], v[168:171], v[0:3]
	s_waitcnt lgkmcnt(6)
	v_mfma_f32_16x16x32_bf16 v[4:7], v[192:195], v[168:171], v[4:7]
	s_waitcnt lgkmcnt(5)
	v_mfma_f32_16x16x32_bf16 v[8:11], v[196:199], v[168:171], v[8:11]
	s_waitcnt lgkmcnt(4)
	v_mfma_f32_16x16x32_bf16 v[12:15], v[200:203], v[168:171], v[12:15]
	s_waitcnt lgkmcnt(3)
	v_mfma_f32_16x16x32_bf16 v[16:19], v[188:191], v[172:175], v[16:19]
	v_mfma_f32_16x16x32_bf16 v[20:23], v[192:195], v[172:175], v[20:23]
	v_mfma_f32_16x16x32_bf16 v[24:27], v[196:199], v[172:175], v[24:27]
	v_mfma_f32_16x16x32_bf16 v[28:31], v[200:203], v[172:175], v[28:31]
	s_waitcnt lgkmcnt(2)
	v_mfma_f32_16x16x32_bf16 v[32:35], v[188:191], v[176:179], v[32:35]
	v_mfma_f32_16x16x32_bf16 v[36:39], v[192:195], v[176:179], v[36:39]
	v_mfma_f32_16x16x32_bf16 v[40:43], v[196:199], v[176:179], v[40:43]
	v_mfma_f32_16x16x32_bf16 v[44:47], v[200:203], v[176:179], v[44:47]
	s_waitcnt lgkmcnt(1)
	v_mfma_f32_16x16x32_bf16 v[48:51], v[188:191], v[180:183], v[48:51]
	v_mfma_f32_16x16x32_bf16 v[52:55], v[192:195], v[180:183], v[52:55]
	v_mfma_f32_16x16x32_bf16 v[56:59], v[196:199], v[180:183], v[56:59]
	v_mfma_f32_16x16x32_bf16 v[60:63], v[200:203], v[180:183], v[60:63]
	s_add_u32 s2, s2, 0x80
	s_addc_u32 s3, s3, 0
	s_add_u32 s6, s6, 0x80
	s_addc_u32 s7, s7, 0
	s_waitcnt lgkmcnt(0)
	v_mfma_f32_16x16x32_bf16 v[64:67], v[188:191], v[184:187], v[64:67]
	v_mfma_f32_16x16x32_bf16 v[68:71], v[192:195], v[184:187], v[68:71]
	v_mfma_f32_16x16x32_bf16 v[72:75], v[196:199], v[184:187], v[72:75]
	v_mfma_f32_16x16x32_bf16 v[76:79], v[200:203], v[184:187], v[76:79]
	s_sub_u32 s12, s12, 1
	s_cmp_lg_u32 s12, 0
	s_cbranch_scc1 .Lgdn0_pair
	s_and_b32 s4, s10, 7
	s_lshl_b32 s4, s4, 3
	s_bfe_u32 s14, s10, 0x30003
	s_or_b32 s14, s14, s4
	s_lshr_b32 s15, s10, 6
	s_mul_i32 s4, s14, 0x50000
	s_lshl_b32 s32, s15, 8
	s_add_u32 s4, s4, s32
	s_add_u32 s8, s78, s4
	s_addc_u32 s9, s79, 0
	s_nop 7
	v_cvt_pk_bf16_f32 v80, v0, v1
	v_cvt_pk_bf16_f32 v81, v2, v3
	v_cvt_pk_bf16_f32 v82, v4, v5
	v_cvt_pk_bf16_f32 v83, v6, v7
	global_store_dwordx4 v217, v[80:83], s[8:9]
	v_cvt_pk_bf16_f32 v84, v8, v9
	v_cvt_pk_bf16_f32 v85, v10, v11
	v_cvt_pk_bf16_f32 v86, v12, v13
	v_cvt_pk_bf16_f32 v87, v14, v15
	global_store_dwordx4 v217, v[84:87], s[8:9] offset:64
	s_add_u32 s8, s8, 0x8000
	s_addc_u32 s9, s9, 0
	v_cvt_pk_bf16_f32 v88, v16, v17
	v_cvt_pk_bf16_f32 v89, v18, v19
	v_cvt_pk_bf16_f32 v90, v20, v21
	v_cvt_pk_bf16_f32 v91, v22, v23
	global_store_dwordx4 v217, v[88:91], s[8:9]
	v_cvt_pk_bf16_f32 v92, v24, v25
	v_cvt_pk_bf16_f32 v93, v26, v27
	v_cvt_pk_bf16_f32 v94, v28, v29
	v_cvt_pk_bf16_f32 v95, v30, v31
	global_store_dwordx4 v217, v[92:95], s[8:9] offset:64
	s_add_u32 s8, s8, 0x8000
	s_addc_u32 s9, s9, 0
	v_cvt_pk_bf16_f32 v96, v32, v33
	v_cvt_pk_bf16_f32 v97, v34, v35
	v_cvt_pk_bf16_f32 v98, v36, v37
	v_cvt_pk_bf16_f32 v99, v38, v39
	global_store_dwordx4 v217, v[96:99], s[8:9]
	v_cvt_pk_bf16_f32 v100, v40, v41
	v_cvt_pk_bf16_f32 v101, v42, v43
	v_cvt_pk_bf16_f32 v102, v44, v45
	v_cvt_pk_bf16_f32 v103, v46, v47
	global_store_dwordx4 v217, v[100:103], s[8:9] offset:64
	s_add_u32 s8, s8, 0x8000
	s_addc_u32 s9, s9, 0
	v_cvt_pk_bf16_f32 v104, v48, v49
	v_cvt_pk_bf16_f32 v105, v50, v51
	v_cvt_pk_bf16_f32 v106, v52, v53
	v_cvt_pk_bf16_f32 v107, v54, v55
	global_store_dwordx4 v217, v[104:107], s[8:9]
	v_cvt_pk_bf16_f32 v108, v56, v57
	v_cvt_pk_bf16_f32 v109, v58, v59
	v_cvt_pk_bf16_f32 v110, v60, v61
	v_cvt_pk_bf16_f32 v111, v62, v63
	global_store_dwordx4 v217, v[108:111], s[8:9] offset:64
	s_add_u32 s8, s8, 0x8000
	s_addc_u32 s9, s9, 0
	v_cvt_pk_bf16_f32 v112, v64, v65
	v_cvt_pk_bf16_f32 v113, v66, v67
	v_cvt_pk_bf16_f32 v114, v68, v69
	v_cvt_pk_bf16_f32 v115, v70, v71
	global_store_dwordx4 v217, v[112:115], s[8:9]
	v_cvt_pk_bf16_f32 v80, v72, v73
	v_cvt_pk_bf16_f32 v81, v74, v75
	v_cvt_pk_bf16_f32 v82, v76, v77
	v_cvt_pk_bf16_f32 v83, v78, v79
	global_store_dwordx4 v217, v[80:83], s[8:9] offset:64
	s_add_u32 s10, s10, s11
	s_cmp_lt_u32 s10, 0x200
	s_cbranch_scc1 .Lgdn0_tile
.Lgdn0_done:
	s_setprio 0
.LBB0_267:
	s_mul_i32 s2, s34, 12
	v_readlane_b32 s20, v162, 12
	s_add_i32 s35, s2, 4
	v_readlane_b32 s21, v162, 13
	s_cmp_ge_i32 s35, s21
	v_readlane_b32 s22, v162, 14
	v_readlane_b32 s23, v162, 15
	s_cbranch_scc1 .LBB0_317
	s_waitcnt vmcnt(0)
	v_readlane_b32 s4, v163, 17
	v_readlane_b32 s5, v163, 18
	s_barrier
	s_and_saveexec_b64 s[2:3], s[4:5]
	s_cbranch_execz .LBB0_316
	s_waitcnt vmcnt(0) expcnt(0) lgkmcnt(0)
	ds_read_b32 v2, v117 offset:53248
	ds_read_b32 v0, v117 offset:53252
	s_waitcnt lgkmcnt(1)
	v_cmp_ne_u32_e32 vcc, 0, v2
	s_cbranch_vccnz .LBB0_284
	s_mov_b32 s36, 1
	s_branch .LBB0_272

.LBB0_375:
	s_andn2_b64 vcc, exec, s[2:3]
	s_cbranch_vccnz .LBB0_521
	v_readlane_b32 s10, v164, 0
	v_readlane_b32 s11, v162, 14
	v_readlane_b32 s16, v163, 15
	v_readlane_b32 s17, v163, 16
	v_readlane_b32 s18, v163, 9
	v_readlane_b32 s19, v163, 10
	s_mul_i32 s4, s34, 0x600000
	s_add_u32 s18, s18, s4
	s_addc_u32 s19, s19, 0
	s_movk_i32 s42, 0x800
	v_and_b32_e32 v220, 63, v128
	v_lshrrev_b32_e32 v221, 6, v128
	v_and_b32_e32 v222, 15, v220
	v_lshrrev_b32_e32 v223, 4, v220
	v_readfirstlane_b32 s40, v221
	v_bfe_u32 v224, v222, 1, 3
	s_lshl_b32 s13, s40, 10
	s_and_b32 s36, s40, 1
	s_lshr_b32 s35, s40, 1
	v_xor_b32_e32 v225, v223, v224
	v_lshlrev_b32_e32 v225, 4, v225
	s_mul_i32 s4, s35, 0x50
	v_add_u32_e32 v226, s4, v222
	v_lshl_add_u32 v204, v226, 7, v225
	v_xor_b32_e32 v205, 64, v204
	s_lshl_b32 s4, s36, 6
	v_add_u32_e32 v227, s4, v222
	v_lshl_add_u32 v206, v227, 7, v225
	v_xor_b32_e32 v207, 64, v206
	v_and_b32_e32 v228, 7, v220
	v_lshrrev_b32_e32 v229, 3, v220
	v_xor_b32_e32 v230, v228, v223
	s_lshl_b32 s4, s36, 2
	v_xor_b32_e32 v230, s4, v230
	v_lshlrev_b32_e32 v230, 4, v230
	s_lshl_b32 s4, s40, 3
	v_add_u32_e32 v231, s4, v229
	v_mad_u32_u24 v208, v231, s42, v230
	v_add_u32_e32 v209, 0x10000, v208
	v_add_u32_e32 v210, 0x20000, v208
	v_add_u32_e32 v211, 0x30000, v208
	v_add_u32_e32 v212, 0x40000, v208
	v_bfe_u32 v232, v231, 2, 2
	v_and_b32_e32 v233, 3, v231
	v_lshrrev_b32_e32 v234, 4, v231
	v_lshl_add_u32 v232, v232, 3, v233
	v_lshl_add_u32 v232, v234, 2, v232
	v_mad_u32_u24 v213, v232, s42, v230
	v_add_u32_e32 v214, 0x10000, v213
	v_add_u32_e32 v215, 0x20000, v213
	v_add_u32_e32 v216, 0x30000, v213
	v_lshlrev_b32_e32 v217, 10, v226
	v_lshl_add_u32 v217, v223, 4, v217
	v_mul_u32_u24_e32 v218, 0x2f00, v226
	v_lshl_add_u32 v218, v223, 5, v218
	s_cmp_ge_u32 s10, 0x600
	s_cbranch_scc1 .Lgzin_done
	s_getreg_b32 s4, hwreg(HW_REG_HW_ID, 0, 4)
	s_and_b32 s4, s4, 1
	s_cmp_eq_u32 s4, 0
	s_cbranch_scc1 .Lgzin_noprio
	s_setprio 1
.Lgzin_noprio:
	s_and_b32 s4, s10, 7
	s_lshl_b32 s4, s4, 3
	s_bfe_u32 s32, s10, 0x30003
	s_or_b32 s4, s4, s32
	s_mul_i32 s4, s4, 0x50000
	s_add_u32 s2, s16, s4
	s_addc_u32 s3, s17, 0
	s_lshr_b32 s4, s10, 6
	s_mul_i32 s4, s4, 0x40000
	s_add_u32 s6, s18, s4
	s_addc_u32 s7, s19, 0
	s_add_u32 m0, s13, 0x0
	s_nop 0
	global_load_lds_dwordx4 v208, s[2:3]
	s_add_u32 m0, s13, 0x1000
	s_nop 0
	global_load_lds_dwordx4 v209, s[2:3]
	s_add_u32 m0, s13, 0x2000
	s_nop 0
	global_load_lds_dwordx4 v210, s[2:3]
	s_add_u32 m0, s13, 0x3000
	s_nop 0
	global_load_lds_dwordx4 v211, s[2:3]
	s_add_u32 m0, s13, 0x4000
	s_nop 0
	global_load_lds_dwordx4 v212, s[2:3]
	s_add_u32 m0, s13, 0x5000
	s_nop 0
	global_load_lds_dwordx4 v213, s[6:7]
	s_add_u32 m0, s13, 0x6000
	s_nop 0
	global_load_lds_dwordx4 v214, s[6:7]
	s_add_u32 m0, s13, 0x7000
	s_nop 0
	global_load_lds_dwordx4 v215, s[6:7]
	s_add_u32 m0, s13, 0x8000
	s_nop 0
	global_load_lds_dwordx4 v216, s[6:7]
	s_add_u32 s2, s2, 0x80
	s_addc_u32 s3, s3, 0
	s_add_u32 s6, s6, 0x80
	s_addc_u32 s7, s7, 0

.Lgzin_z1_end:
	s_add_u32 s10, s10, s11
	s_cmp_lt_u32 s10, 0x600
	s_cbranch_scc1 .Lgzin_tile
.Lgzin_done:
	s_setprio 0
.LBB0_471:
	s_mul_i32 s2, s34, 12
	v_readlane_b32 s20, v162, 12
	s_add_i32 s35, s2, 6
	v_readlane_b32 s21, v162, 13
	s_cmp_ge_i32 s35, s21
	v_readlane_b32 s22, v162, 14
	v_readlane_b32 s23, v162, 15
	s_cbranch_scc1 .LBB0_521
	s_waitcnt vmcnt(0)
	v_readlane_b32 s4, v163, 17
	v_readlane_b32 s5, v163, 18
	s_barrier
	s_and_saveexec_b64 s[2:3], s[4:5]
	s_cbranch_execz .LBB0_520
	s_waitcnt vmcnt(0) expcnt(0) lgkmcnt(0)
	ds_read_b32 v2, v117 offset:53248
	ds_read_b32 v0, v117 offset:53252
	s_waitcnt lgkmcnt(1)
	v_cmp_ne_u32_e32 vcc, 0, v2
	s_cbranch_vccnz .LBB0_488
	s_mov_b32 s36, 1
	s_branch .LBB0_476

.LBB0_859:
	s_andn2_b64 vcc, exec, s[2:3]
	s_cbranch_vccnz .LBB0_927
	v_readlane_b32 s10, v164, 0
	v_readlane_b32 s11, v162, 14
	s_mov_b32 s16, s80
	s_mov_b32 s17, s81
	v_readlane_b32 s18, v163, 11
	v_readlane_b32 s19, v163, 12
	s_mul_i32 s4, s34, 0x200000
	s_add_u32 s18, s18, s4
	s_addc_u32 s19, s19, 0
	s_movk_i32 s42, 0x800
	v_and_b32_e32 v220, 63, v128
	v_lshrrev_b32_e32 v221, 6, v128
	v_and_b32_e32 v222, 15, v220
	v_lshrrev_b32_e32 v223, 4, v220
	v_readfirstlane_b32 s40, v221
	v_bfe_u32 v224, v222, 1, 3
	s_lshl_b32 s13, s40, 10
	s_and_b32 s36, s40, 1
	s_lshr_b32 s35, s40, 1
	v_xor_b32_e32 v225, v223, v224
	v_lshlrev_b32_e32 v225, 4, v225
	s_mul_i32 s4, s35, 0x50
	v_add_u32_e32 v226, s4, v222
	v_lshl_add_u32 v204, v226, 7, v225
	v_xor_b32_e32 v205, 64, v204
	s_lshl_b32 s4, s36, 6
	v_add_u32_e32 v227, s4, v222
	v_lshl_add_u32 v206, v227, 7, v225
	v_xor_b32_e32 v207, 64, v206
	v_and_b32_e32 v228, 7, v220
	v_lshrrev_b32_e32 v229, 3, v220
	v_xor_b32_e32 v230, v228, v223
	s_lshl_b32 s4, s36, 2
	v_xor_b32_e32 v230, s4, v230
	v_lshlrev_b32_e32 v230, 4, v230
	s_lshl_b32 s4, s40, 3
	v_add_u32_e32 v231, s4, v229
	v_mad_u32_u24 v208, v231, s42, v230
	v_add_u32_e32 v209, 0x10000, v208
	v_add_u32_e32 v210, 0x20000, v208
	v_add_u32_e32 v211, 0x30000, v208
	v_add_u32_e32 v212, 0x40000, v208
	v_bfe_u32 v232, v231, 2, 2
	v_and_b32_e32 v233, 3, v231
	v_lshrrev_b32_e32 v234, 4, v231
	v_lshl_add_u32 v232, v232, 3, v233
	v_lshl_add_u32 v232, v234, 2, v232
	v_mad_u32_u24 v213, v232, s42, v230
	v_add_u32_e32 v214, 0x10000, v213
	v_add_u32_e32 v215, 0x20000, v213
	v_add_u32_e32 v216, 0x30000, v213
	v_lshlrev_b32_e32 v217, 11, v226
	v_lshl_add_u32 v217, v223, 4, v217
	s_lshl_b32 s4, s36, 7
	v_add_u32_e32 v217, s4, v217
	s_cmp_ge_u32 s10, 0x200
	s_cbranch_scc1 .Lgout_done
	s_getreg_b32 s4, hwreg(HW_REG_HW_ID, 0, 4)
	s_and_b32 s4, s4, 1
	s_cmp_eq_u32 s4, 0
	s_cbranch_scc1 .Lgout_noprio
	s_setprio 1

.Lgout_pair:
	s_waitcnt vmcnt(0)
	s_barrier
	ds_read_b128 v[80:83], v204 offset:0
	ds_read_b128 v[100:103], v206 offset:20480
	ds_read_b128 v[104:107], v206 offset:22528
	ds_read_b128 v[108:111], v206 offset:24576
	ds_read_b128 v[112:115], v206 offset:26624
	ds_read_b128 v[84:87], v204 offset:2048
	ds_read_b128 v[88:91], v204 offset:4096
	ds_read_b128 v[92:95], v204 offset:6144
	ds_read_b128 v[96:99], v204 offset:8192
	s_add_u32 m0, s13, 0xd100
	s_waitcnt lgkmcnt(7)
	v_mfma_f32_16x16x32_bf16 v[0:3], v[100:103], v[80:83], v[0:3]
	global_load_lds_dwordx4 v208, s[2:3]
	s_add_u32 m0, s13, 0xe100
	s_waitcnt lgkmcnt(6)
	v_mfma_f32_16x16x32_bf16 v[4:7], v[104:107], v[80:83], v[4:7]
	global_load_lds_dwordx4 v209, s[2:3]
	s_add_u32 m0, s13, 0xf100
	s_waitcnt lgkmcnt(5)
	v_mfma_f32_16x16x32_bf16 v[8:11], v[108:111], v[80:83], v[8:11]
	global_load_lds_dwordx4 v210, s[2:3]
	s_add_u32 m0, s13, 0x10100
	s_waitcnt lgkmcnt(4)
	v_mfma_f32_16x16x32_bf16 v[12:15], v[112:115], v[80:83], v[12:15]
	global_load_lds_dwordx4 v211, s[2:3]
	s_add_u32 m0, s13, 0x11100
	ds_read_b128 v[168:171], v205 offset:0
	ds_read_b128 v[188:191], v207 offset:20480
	ds_read_b128 v[192:195], v207 offset:22528
	ds_read_b128 v[196:199], v207 offset:24576
	ds_read_b128 v[200:203], v207 offset:26624
	s_waitcnt lgkmcnt(8)
	v_mfma_f32_16x16x32_bf16 v[16:19], v[100:103], v[84:87], v[16:19]
	global_load_lds_dwordx4 v212, s[2:3]
	s_add_u32 m0, s13, 0x9000
	v_mfma_f32_16x16x32_bf16 v[20:23], v[104:107], v[84:87], v[20:23]
	global_load_lds_dwordx4 v213, s[6:7]
	s_add_u32 m0, s13, 0xa000
	v_mfma_f32_16x16x32_bf16 v[24:27], v[108:111], v[84:87], v[24:27]
	global_load_lds_dwordx4 v214, s[6:7]
	s_add_u32 m0, s13, 0xb000
	v_mfma_f32_16x16x32_bf16 v[28:31], v[112:115], v[84:87], v[28:31]
	global_load_lds_dwordx4 v215, s[6:7]
	s_add_u32 m0, s13, 0xc000
	ds_read_b128 v[172:175], v205 offset:2048
	ds_read_b128 v[176:179], v205 offset:4096
	ds_read_b128 v[180:183], v205 offset:6144
	ds_read_b128 v[184:187], v205 offset:8192
	s_waitcnt lgkmcnt(11)
	v_mfma_f32_16x16x32_bf16 v[32:35], v[100:103], v[88:91], v[32:35]
	global_load_lds_dwordx4 v216, s[6:7]
	v_mfma_f32_16x16x32_bf16 v[36:39], v[104:107], v[88:91], v[36:39]
	v_mfma_f32_16x16x32_bf16 v[40:43], v[108:111], v[88:91], v[40:43]
	v_mfma_f32_16x16x32_bf16 v[44:47], v[112:115], v[88:91], v[44:47]
	s_waitcnt lgkmcnt(10)
	v_mfma_f32_16x16x32_bf16 v[48:51], v[100:103], v[92:95], v[48:51]
	v_mfma_f32_16x16x32_bf16 v[52:55], v[104:107], v[92:95], v[52:55]
	v_mfma_f32_16x16x32_bf16 v[56:59], v[108:111], v[92:95], v[56:59]
	v_mfma_f32_16x16x32_bf16 v[60:63], v[112:115], v[92:95], v[60:63]
	s_waitcnt lgkmcnt(9)
	v_mfma_f32_16x16x32_bf16 v[64:67], v[100:103], v[96:99], v[64:67]
	v_mfma_f32_16x16x32_bf16 v[68:71], v[104:107], v[96:99], v[68:71]
	v_mfma_f32_16x16x32_bf16 v[72:75], v[108:111], v[96:99], v[72:75]
	v_mfma_f32_16x16x32_bf16 v[76:79], v[112:115], v[96:99], v[76:79]
	s_waitcnt lgkmcnt(7)
	v_mfma_f32_16x16x32_bf16 v[0:3], v[188:191], v[168:171], v[0:3]
	s_waitcnt lgkmcnt(6)
	v_mfma_f32_16x16x32_bf16 v[4:7], v[192:195], v[168:171], v[4:7]
	s_waitcnt lgkmcnt(5)
	v_mfma_f32_16x16x32_bf16 v[8:11], v[196:199], v[168:171], v[8:11]
	s_waitcnt lgkmcnt(4)
	v_mfma_f32_16x16x32_bf16 v[12:15], v[200:203], v[168:171], v[12:15]
	s_waitcnt lgkmcnt(3)
	v_mfma_f32_16x16x32_bf16 v[16:19], v[188:191], v[172:175], v[16:19]
	v_mfma_f32_16x16x32_bf16 v[20:23], v[192:195], v[172:175], v[20:23]
	v_mfma_f32_16x16x32_bf16 v[24:27], v[196:199], v[172:175], v[24:27]
	v_mfma_f32_16x16x32_bf16 v[28:31], v[200:203], v[172:175], v[28:31]
	s_waitcnt lgkmcnt(2)
	v_mfma_f32_16x16x32_bf16 v[32:35], v[188:191], v[176:179], v[32:35]
	v_mfma_f32_16x16x32_bf16 v[36:39], v[192:195], v[176:179], v[36:39]
	v_mfma_f32_16x16x32_bf16 v[40:43], v[196:199], v[176:179], v[40:43]
	v_mfma_f32_16x16x32_bf16 v[44:47], v[200:203], v[176:179], v[44:47]
	s_waitcnt lgkmcnt(1)
	v_mfma_f32_16x16x32_bf16 v[48:51], v[188:191], v[180:183], v[48:51]
	v_mfma_f32_16x16x32_bf16 v[52:55], v[192:195], v[180:183], v[52:55]
	v_mfma_f32_16x16x32_bf16 v[56:59], v[196:199], v[180:183], v[56:59]
	v_mfma_f32_16x16x32_bf16 v[60:63], v[200:203], v[180:183], v[60:63]
	s_add_u32 s2, s2, 0x80
	s_addc_u32 s3, s3, 0
	s_add_u32 s6, s6, 0x80
	s_addc_u32 s7, s7, 0
	s_waitcnt lgkmcnt(0)
	v_mfma_f32_16x16x32_bf16 v[64:67], v[188:191], v[184:187], v[64:67]
	v_mfma_f32_16x16x32_bf16 v[68:71], v[192:195], v[184:187], v[68:71]
	v_mfma_f32_16x16x32_bf16 v[72:75], v[196:199], v[184:187], v[72:75]
	v_mfma_f32_16x16x32_bf16 v[76:79], v[200:203], v[184:187], v[76:79]
	s_cmp_eq_u32 s12, 1
	s_cselect_b32 s2, s20, s2
	s_cselect_b32 s3, s21, s3
	s_cselect_b32 s6, s22, s6
	s_cselect_b32 s7, s23, s7
	s_waitcnt vmcnt(0)
	s_barrier
	ds_read_b128 v[80:83], v204 offset:53504
	ds_read_b128 v[100:103], v206 offset:36864
	ds_read_b128 v[104:107], v206 offset:38912
	ds_read_b128 v[108:111], v206 offset:40960
	ds_read_b128 v[112:115], v206 offset:43008
	ds_read_b128 v[84:87], v204 offset:55552
	ds_read_b128 v[88:91], v204 offset:57600
	ds_read_b128 v[92:95], v204 offset:59648
	ds_read_b128 v[96:99], v204 offset:61696
	s_add_u32 m0, s13, 0x0
	s_waitcnt lgkmcnt(7)
	v_mfma_f32_16x16x32_bf16 v[0:3], v[100:103], v[80:83], v[0:3]
	global_load_lds_dwordx4 v208, s[2:3]
	s_add_u32 m0, s13, 0x1000
	s_waitcnt lgkmcnt(6)
	v_mfma_f32_16x16x32_bf16 v[4:7], v[104:107], v[80:83], v[4:7]
	global_load_lds_dwordx4 v209, s[2:3]
	s_add_u32 m0, s13, 0x2000
	s_waitcnt lgkmcnt(5)
	v_mfma_f32_16x16x32_bf16 v[8:11], v[108:111], v[80:83], v[8:11]
	global_load_lds_dwordx4 v210, s[2:3]
	s_add_u32 m0, s13, 0x3000
	s_waitcnt lgkmcnt(4)
	v_mfma_f32_16x16x32_bf16 v[12:15], v[112:115], v[80:83], v[12:15]
	global_load_lds_dwordx4 v211, s[2:3]
	s_add_u32 m0, s13, 0x4000
	ds_read_b128 v[168:171], v205 offset:53504
	ds_read_b128 v[188:191], v207 offset:36864
	ds_read_b128 v[192:195], v207 offset:38912
	ds_read_b128 v[196:199], v207 offset:40960
	ds_read_b128 v[200:203], v207 offset:43008
	s_waitcnt lgkmcnt(8)
	v_mfma_f32_16x16x32_bf16 v[16:19], v[100:103], v[84:87], v[16:19]
	global_load_lds_dwordx4 v212, s[2:3]
	s_add_u32 m0, s13, 0x5000
	v_mfma_f32_16x16x32_bf16 v[20:23], v[104:107], v[84:87], v[20:23]
	global_load_lds_dwordx4 v213, s[6:7]
	s_add_u32 m0, s13, 0x6000
	v_mfma_f32_16x16x32_bf16 v[24:27], v[108:111], v[84:87], v[24:27]
	global_load_lds_dwordx4 v214, s[6:7]
	s_add_u32 m0, s13, 0x7000
	v_mfma_f32_16x16x32_bf16 v[28:31], v[112:115], v[84:87], v[28:31]
	global_load_lds_dwordx4 v215, s[6:7]
	s_add_u32 m0, s13, 0x8000
	ds_read_b128 v[172:175], v205 offset:55552
	ds_read_b128 v[176:179], v205 offset:57600
	ds_read_b128 v[180:183], v205 offset:59648
	ds_read_b128 v[184:187], v205 offset:61696
	s_waitcnt lgkmcnt(11)
	v_mfma_f32_16x16x32_bf16 v[32:35], v[100:103], v[88:91], v[32:35]
	global_load_lds_dwordx4 v216, s[6:7]
	v_mfma_f32_16x16x32_bf16 v[36:39], v[104:107], v[88:91], v[36:39]
	v_mfma_f32_16x16x32_bf16 v[40:43], v[108:111], v[88:91], v[40:43]
	v_mfma_f32_16x16x32_bf16 v[44:47], v[112:115], v[88:91], v[44:47]
	s_waitcnt lgkmcnt(10)
	v_mfma_f32_16x16x32_bf16 v[48:51], v[100:103], v[92:95], v[48:51]
	v_mfma_f32_16x16x32_bf16 v[52:55], v[104:107], v[92:95], v[52:55]
	v_mfma_f32_16x16x32_bf16 v[56:59], v[108:111], v[92:95], v[56:59]
	v_mfma_f32_16x16x32_bf16 v[60:63], v[112:115], v[92:95], v[60:63]
	s_waitcnt lgkmcnt(9)
	v_mfma_f32_16x16x32_bf16 v[64:67], v[100:103], v[96:99], v[64:67]
	v_mfma_f32_16x16x32_bf16 v[68:71], v[104:107], v[96:99], v[68:71]
	v_mfma_f32_16x16x32_bf16 v[72:75], v[108:111], v[96:99], v[72:75]
	v_mfma_f32_16x16x32_bf16 v[76:79], v[112:115], v[96:99], v[76:79]
	s_waitcnt lgkmcnt(7)
	v_mfma_f32_16x16x32_bf16 v[0:3], v[188:191], v[168:171], v[0:3]
	s_waitcnt lgkmcnt(6)
	v_mfma_f32_16x16x32_bf16 v[4:7], v[192:195], v[168:171], v[4:7]
	s_waitcnt lgkmcnt(5)
	v_mfma_f32_16x16x32_bf16 v[8:11], v[196:199], v[168:171], v[8:11]
	s_waitcnt lgkmcnt(4)
	v_mfma_f32_16x16x32_bf16 v[12:15], v[200:203], v[168:171], v[12:15]
	s_waitcnt lgkmcnt(3)
	v_mfma_f32_16x16x32_bf16 v[16:19], v[188:191], v[172:175], v[16:19]
	v_mfma_f32_16x16x32_bf16 v[20:23], v[192:195], v[172:175], v[20:23]
	v_mfma_f32_16x16x32_bf16 v[24:27], v[196:199], v[172:175], v[24:27]
	v_mfma_f32_16x16x32_bf16 v[28:31], v[200:203], v[172:175], v[28:31]
	s_waitcnt lgkmcnt(2)
	v_mfma_f32_16x16x32_bf16 v[32:35], v[188:191], v[176:179], v[32:35]
	v_mfma_f32_16x16x32_bf16 v[36:39], v[192:195], v[176:179], v[36:39]
	v_mfma_f32_16x16x32_bf16 v[40:43], v[196:199], v[176:179], v[40:43]
	v_mfma_f32_16x16x32_bf16 v[44:47], v[200:203], v[176:179], v[44:47]
	s_waitcnt lgkmcnt(1)
	v_mfma_f32_16x16x32_bf16 v[48:51], v[188:191], v[180:183], v[48:51]
	v_mfma_f32_16x16x32_bf16 v[52:55], v[192:195], v[180:183], v[52:55]
	v_mfma_f32_16x16x32_bf16 v[56:59], v[196:199], v[180:183], v[56:59]
	v_mfma_f32_16x16x32_bf16 v[60:63], v[200:203], v[180:183], v[60:63]
	s_add_u32 s2, s2, 0x80
	s_addc_u32 s3, s3, 0
	s_add_u32 s6, s6, 0x80
	s_addc_u32 s7, s7, 0
	s_waitcnt lgkmcnt(0)
	v_mfma_f32_16x16x32_bf16 v[64:67], v[188:191], v[184:187], v[64:67]
	v_mfma_f32_16x16x32_bf16 v[68:71], v[192:195], v[184:187], v[68:71]
	v_mfma_f32_16x16x32_bf16 v[72:75], v[196:199], v[184:187], v[72:75]
	v_mfma_f32_16x16x32_bf16 v[76:79], v[200:203], v[184:187], v[76:79]
	s_sub_u32 s12, s12, 1
	s_cmp_lg_u32 s12, 0
	s_cbranch_scc1 .Lgout_pair
	s_and_b32 s4, s10, 7
	s_lshl_b32 s4, s4, 3
	s_bfe_u32 s14, s10, 0x30003
	s_or_b32 s14, s14, s4
	s_lshr_b32 s15, s10, 6
	s_mul_i32 s4, s14, 0x50000
	s_lshl_b32 s32, s15, 8
	s_add_u32 s4, s4, s32
	s_add_u32 s8, s78, s4
	s_addc_u32 s9, s79, 0
	s_nop 7
	v_cvt_pk_bf16_f32 v80, v0, v1
	v_cvt_pk_bf16_f32 v81, v2, v3
	v_cvt_pk_bf16_f32 v82, v4, v5
	v_cvt_pk_bf16_f32 v83, v6, v7
	global_store_dwordx4 v217, v[80:83], s[8:9]
	v_cvt_pk_bf16_f32 v84, v8, v9
	v_cvt_pk_bf16_f32 v85, v10, v11
	v_cvt_pk_bf16_f32 v86, v12, v13
	v_cvt_pk_bf16_f32 v87, v14, v15
	global_store_dwordx4 v217, v[84:87], s[8:9] offset:64
	s_add_u32 s8, s8, 0x8000
	s_addc_u32 s9, s9, 0
	v_cvt_pk_bf16_f32 v88, v16, v17
	v_cvt_pk_bf16_f32 v89, v18, v19
	v_cvt_pk_bf16_f32 v90, v20, v21
	v_cvt_pk_bf16_f32 v91, v22, v23
	global_store_dwordx4 v217, v[88:91], s[8:9]
	v_cvt_pk_bf16_f32 v92, v24, v25
	v_cvt_pk_bf16_f32 v93, v26, v27
	v_cvt_pk_bf16_f32 v94, v28, v29
	v_cvt_pk_bf16_f32 v95, v30, v31
	global_store_dwordx4 v217, v[92:95], s[8:9] offset:64
	s_add_u32 s8, s8, 0x8000
	s_addc_u32 s9, s9, 0
	v_cvt_pk_bf16_f32 v96, v32, v33
	v_cvt_pk_bf16_f32 v97, v34, v35
	v_cvt_pk_bf16_f32 v98, v36, v37
	v_cvt_pk_bf16_f32 v99, v38, v39
	global_store_dwordx4 v217, v[96:99], s[8:9]
	v_cvt_pk_bf16_f32 v100, v40, v41
	v_cvt_pk_bf16_f32 v101, v42, v43
	v_cvt_pk_bf16_f32 v102, v44, v45
	v_cvt_pk_bf16_f32 v103, v46, v47
	global_store_dwordx4 v217, v[100:103], s[8:9] offset:64
	s_add_u32 s8, s8, 0x8000
	s_addc_u32 s9, s9, 0
	v_cvt_pk_bf16_f32 v104, v48, v49
	v_cvt_pk_bf16_f32 v105, v50, v51
	v_cvt_pk_bf16_f32 v106, v52, v53
	v_cvt_pk_bf16_f32 v107, v54, v55
	global_store_dwordx4 v217, v[104:107], s[8:9]
	v_cvt_pk_bf16_f32 v108, v56, v57
	v_cvt_pk_bf16_f32 v109, v58, v59
	v_cvt_pk_bf16_f32 v110, v60, v61
	v_cvt_pk_bf16_f32 v111, v62, v63
	global_store_dwordx4 v217, v[108:111], s[8:9] offset:64
	s_add_u32 s8, s8, 0x8000
	s_addc_u32 s9, s9, 0
	v_cvt_pk_bf16_f32 v112, v64, v65
	v_cvt_pk_bf16_f32 v113, v66, v67
	v_cvt_pk_bf16_f32 v114, v68, v69
	v_cvt_pk_bf16_f32 v115, v70, v71
	global_store_dwordx4 v217, v[112:115], s[8:9]
	v_cvt_pk_bf16_f32 v80, v72, v73
	v_cvt_pk_bf16_f32 v81, v74, v75
	v_cvt_pk_bf16_f32 v82, v76, v77
	v_cvt_pk_bf16_f32 v83, v78, v79
	global_store_dwordx4 v217, v[80:83], s[8:9] offset:64
	s_add_u32 s10, s10, s11
	s_cmp_lt_u32 s10, 0x200
	s_cbranch_scc1 .Lgout_tile
.Lgout_done:
	s_setprio 0
.LBB0_877:
	v_readlane_b32 s2, v162, 36
	v_readlane_b32 s20, v162, 12
	s_add_i32 s35, s2, 10
	v_readlane_b32 s21, v162, 13
	s_cmp_ge_i32 s35, s21
	v_readlane_b32 s22, v162, 14
	v_readlane_b32 s23, v162, 15
	s_cbranch_scc1 .LBB0_927
	s_waitcnt vmcnt(0)
	v_readlane_b32 s4, v163, 17
	v_readlane_b32 s5, v163, 18
	s_barrier
	s_and_saveexec_b64 s[2:3], s[4:5]
	s_cbranch_execz .LBB0_926
	s_waitcnt vmcnt(0) expcnt(0) lgkmcnt(0)
	ds_read_b32 v2, v117 offset:53248
	ds_read_b32 v0, v117 offset:53252
	s_waitcnt lgkmcnt(1)
	v_cmp_ne_u32_e32 vcc, 0, v2
	s_cbranch_vccnz .LBB0_894
	s_mov_b32 s36, 1
	s_branch .LBB0_882

.LBB0_985:
	s_andn2_b64 vcc, exec, s[2:3]
	s_cbranch_vccnz .LBB0_1041
	v_readlane_b32 s10, v164, 0
	v_readlane_b32 s11, v162, 14
	v_readlane_b32 s16, v163, 15
	v_readlane_b32 s17, v163, 16
	v_readlane_b32 s18, v163, 5
	v_readlane_b32 s19, v163, 6
	s_mul_i32 s4, s34, 0x1600000
	s_add_u32 s18, s18, s4
	s_addc_u32 s19, s19, 0
	s_add_u32 s18, s18, 0xb00000
	s_addc_u32 s19, s19, 0
	s_movk_i32 s42, 0x800
	v_and_b32_e32 v220, 63, v128
	v_lshrrev_b32_e32 v221, 6, v128
	v_and_b32_e32 v222, 15, v220
	v_lshrrev_b32_e32 v223, 4, v220
	v_readfirstlane_b32 s40, v221
	v_bfe_u32 v224, v222, 1, 3
	s_lshl_b32 s13, s40, 10
	s_and_b32 s36, s40, 1
	s_lshr_b32 s35, s40, 1
	v_xor_b32_e32 v225, v223, v224
	v_lshlrev_b32_e32 v225, 4, v225
	s_mul_i32 s4, s35, 0x50
	v_add_u32_e32 v226, s4, v222
	v_lshl_add_u32 v116, v226, 7, v225
	v_xor_b32_e32 v118, 64, v116
	s_lshl_b32 s4, s36, 6
	v_add_u32_e32 v227, s4, v222
	v_lshl_add_u32 v119, v227, 7, v225
	v_xor_b32_e32 v160, 64, v119
	v_and_b32_e32 v228, 7, v220
	v_lshrrev_b32_e32 v229, 3, v220
	v_xor_b32_e32 v230, v228, v223
	s_lshl_b32 s4, s36, 2
	v_xor_b32_e32 v230, s4, v230
	v_lshlrev_b32_e32 v230, 4, v230
	s_lshl_b32 s4, s40, 3
	v_add_u32_e32 v231, s4, v229
	v_mad_u32_u24 v161, v231, s42, v230
	v_bfe_u32 v232, v231, 2, 2
	v_and_b32_e32 v233, 3, v231
	v_lshrrev_b32_e32 v234, 4, v231
	v_lshl_add_u32 v232, v232, 3, v233
	s_movk_i32 s4, 0xb00
	v_mad_u32_u24 v232, v234, s4, v232
	v_mad_u32_u24 v165, v232, s42, v230
	v_mul_u32_u24_e32 v167, 0x1600, v226
	v_lshl_add_u32 v167, v223, 4, v167
	s_lshl_b32 s4, s36, 6
	v_add_u32_e32 v167, s4, v167
	s_cmp_ge_u32 s10, 0x580
	s_cbranch_scc1 .Lggu1_done
	s_getreg_b32 s4, hwreg(HW_REG_HW_ID, 0, 4)
	s_and_b32 s4, s4, 1
	s_cmp_eq_u32 s4, 0
	s_cbranch_scc1 .Lggu1_noprio
	s_setprio 1

.Lggu1_done:
	s_setprio 0
.LBB0_991:
	v_readlane_b32 s2, v162, 36
	v_readlane_b32 s20, v162, 12
	s_add_i32 s35, s2, 12
	v_readlane_b32 s21, v162, 13
	s_cmp_ge_i32 s35, s21
	v_readlane_b32 s22, v162, 14
	v_readlane_b32 s23, v162, 15
	s_cbranch_scc1 .LBB0_1041
	s_waitcnt vmcnt(0)
	v_readlane_b32 s4, v163, 17
	v_readlane_b32 s5, v163, 18
	s_barrier
	s_and_saveexec_b64 s[2:3], s[4:5]
	s_cbranch_execz .LBB0_1040
	s_waitcnt vmcnt(0) expcnt(0) lgkmcnt(0)
	ds_read_b32 v2, v117 offset:53248
	ds_read_b32 v0, v117 offset:53252
	s_waitcnt lgkmcnt(1)
	v_cmp_ne_u32_e32 vcc, 0, v2
	s_cbranch_vccnz .LBB0_1008
	s_mov_b32 s36, 1
	s_branch .LBB0_996

.LBB0_1043:
	s_andn2_b64 vcc, exec, s[2:3]
	s_cbranch_vccnz .LBB0_1111
	v_readlane_b32 s10, v164, 0
	v_readlane_b32 s11, v162, 14
	s_mov_b32 s16, s76
	s_mov_b32 s17, s77
	v_readlane_b32 s18, v163, 7
	v_readlane_b32 s19, v163, 8
	s_mul_i32 s4, s34, 0xb00000
	s_add_u32 s18, s18, s4
	s_addc_u32 s19, s19, 0
	s_add_u32 s18, s18, 0x580000
	s_addc_u32 s19, s19, 0
	s_movk_i32 s42, 0x1600
	v_and_b32_e32 v220, 63, v128
	v_lshrrev_b32_e32 v221, 6, v128
	v_and_b32_e32 v222, 15, v220
	v_lshrrev_b32_e32 v223, 4, v220
	v_readfirstlane_b32 s40, v221
	v_bfe_u32 v224, v222, 1, 3
	s_lshl_b32 s13, s40, 10
	s_and_b32 s36, s40, 1
	s_lshr_b32 s35, s40, 1
	v_xor_b32_e32 v225, v223, v224
	v_lshlrev_b32_e32 v225, 4, v225
	s_mul_i32 s4, s35, 0x50
	v_add_u32_e32 v226, s4, v222
	v_lshl_add_u32 v204, v226, 7, v225
	v_xor_b32_e32 v205, 64, v204
	s_lshl_b32 s4, s36, 6
	v_add_u32_e32 v227, s4, v222
	v_lshl_add_u32 v206, v227, 7, v225
	v_xor_b32_e32 v207, 64, v206
	v_and_b32_e32 v228, 7, v220
	v_lshrrev_b32_e32 v229, 3, v220
	v_xor_b32_e32 v230, v228, v223
	s_lshl_b32 s4, s36, 2
	v_xor_b32_e32 v230, s4, v230
	v_lshlrev_b32_e32 v230, 4, v230
	s_lshl_b32 s4, s40, 3
	v_add_u32_e32 v231, s4, v229
	v_mad_u32_u24 v208, v231, s42, v230
	v_add_u32_e32 v209, 0x2c000, v208
	v_add_u32_e32 v210, 0x58000, v208
	v_add_u32_e32 v211, 0x84000, v208
	v_add_u32_e32 v212, 0xb0000, v208
	v_bfe_u32 v232, v231, 2, 2
	v_and_b32_e32 v233, 3, v231
	v_lshrrev_b32_e32 v234, 4, v231
	v_lshl_add_u32 v232, v232, 3, v233
	v_lshl_add_u32 v232, v234, 2, v232
	v_mad_u32_u24 v213, v232, s42, v230
	v_add_u32_e32 v214, 0x2c000, v213
	v_add_u32_e32 v215, 0x58000, v213
	v_add_u32_e32 v216, 0x84000, v213
	v_lshlrev_b32_e32 v217, 11, v226
	v_lshl_add_u32 v217, v223, 4, v217
	s_lshl_b32 s4, s36, 7
	v_add_u32_e32 v217, s4, v217
	s_cmp_ge_u32 s10, 0x200
	s_cbranch_scc1 .Lgdn1_done
	s_getreg_b32 s4, hwreg(HW_REG_HW_ID, 0, 4)
	s_and_b32 s4, s4, 1
	s_cmp_eq_u32 s4, 0
	s_cbranch_scc1 .Lgdn1_noprio
	s_setprio 1

.Lgdn1_pair:
	s_waitcnt vmcnt(0)
	s_barrier
	ds_read_b128 v[80:83], v204 offset:0
	ds_read_b128 v[100:103], v206 offset:20480
	ds_read_b128 v[104:107], v206 offset:22528
	ds_read_b128 v[108:111], v206 offset:24576
	ds_read_b128 v[112:115], v206 offset:26624
	ds_read_b128 v[84:87], v204 offset:2048
	ds_read_b128 v[88:91], v204 offset:4096
	ds_read_b128 v[92:95], v204 offset:6144
	ds_read_b128 v[96:99], v204 offset:8192
	s_add_u32 m0, s13, 0xd100
	s_waitcnt lgkmcnt(7)
	v_mfma_f32_16x16x32_bf16 v[0:3], v[100:103], v[80:83], v[0:3]
	global_load_lds_dwordx4 v208, s[2:3]
	s_add_u32 m0, s13, 0xe100
	s_waitcnt lgkmcnt(6)
	v_mfma_f32_16x16x32_bf16 v[4:7], v[104:107], v[80:83], v[4:7]
	global_load_lds_dwordx4 v209, s[2:3]
	s_add_u32 m0, s13, 0xf100
	s_waitcnt lgkmcnt(5)
	v_mfma_f32_16x16x32_bf16 v[8:11], v[108:111], v[80:83], v[8:11]
	global_load_lds_dwordx4 v210, s[2:3]
	s_add_u32 m0, s13, 0x10100
	s_waitcnt lgkmcnt(4)
	v_mfma_f32_16x16x32_bf16 v[12:15], v[112:115], v[80:83], v[12:15]
	global_load_lds_dwordx4 v211, s[2:3]
	s_add_u32 m0, s13, 0x11100
	ds_read_b128 v[168:171], v205 offset:0
	ds_read_b128 v[188:191], v207 offset:20480
	ds_read_b128 v[192:195], v207 offset:22528
	ds_read_b128 v[196:199], v207 offset:24576
	ds_read_b128 v[200:203], v207 offset:26624
	s_waitcnt lgkmcnt(8)
	v_mfma_f32_16x16x32_bf16 v[16:19], v[100:103], v[84:87], v[16:19]
	global_load_lds_dwordx4 v212, s[2:3]
	s_add_u32 m0, s13, 0x9000
	v_mfma_f32_16x16x32_bf16 v[20:23], v[104:107], v[84:87], v[20:23]
	global_load_lds_dwordx4 v213, s[6:7]
	s_add_u32 m0, s13, 0xa000
	v_mfma_f32_16x16x32_bf16 v[24:27], v[108:111], v[84:87], v[24:27]
	global_load_lds_dwordx4 v214, s[6:7]
	s_add_u32 m0, s13, 0xb000
	v_mfma_f32_16x16x32_bf16 v[28:31], v[112:115], v[84:87], v[28:31]
	global_load_lds_dwordx4 v215, s[6:7]
	s_add_u32 m0, s13, 0xc000
	ds_read_b128 v[172:175], v205 offset:2048
	ds_read_b128 v[176:179], v205 offset:4096
	ds_read_b128 v[180:183], v205 offset:6144
	ds_read_b128 v[184:187], v205 offset:8192
	s_waitcnt lgkmcnt(11)
	v_mfma_f32_16x16x32_bf16 v[32:35], v[100:103], v[88:91], v[32:35]
	global_load_lds_dwordx4 v216, s[6:7]
	v_mfma_f32_16x16x32_bf16 v[36:39], v[104:107], v[88:91], v[36:39]
	v_mfma_f32_16x16x32_bf16 v[40:43], v[108:111], v[88:91], v[40:43]
	v_mfma_f32_16x16x32_bf16 v[44:47], v[112:115], v[88:91], v[44:47]
	s_waitcnt lgkmcnt(10)
	v_mfma_f32_16x16x32_bf16 v[48:51], v[100:103], v[92:95], v[48:51]
	v_mfma_f32_16x16x32_bf16 v[52:55], v[104:107], v[92:95], v[52:55]
	v_mfma_f32_16x16x32_bf16 v[56:59], v[108:111], v[92:95], v[56:59]
	v_mfma_f32_16x16x32_bf16 v[60:63], v[112:115], v[92:95], v[60:63]
	s_waitcnt lgkmcnt(9)
	v_mfma_f32_16x16x32_bf16 v[64:67], v[100:103], v[96:99], v[64:67]
	v_mfma_f32_16x16x32_bf16 v[68:71], v[104:107], v[96:99], v[68:71]
	v_mfma_f32_16x16x32_bf16 v[72:75], v[108:111], v[96:99], v[72:75]
	v_mfma_f32_16x16x32_bf16 v[76:79], v[112:115], v[96:99], v[76:79]
	s_waitcnt lgkmcnt(7)
	v_mfma_f32_16x16x32_bf16 v[0:3], v[188:191], v[168:171], v[0:3]
	s_waitcnt lgkmcnt(6)
	v_mfma_f32_16x16x32_bf16 v[4:7], v[192:195], v[168:171], v[4:7]
	s_waitcnt lgkmcnt(5)
	v_mfma_f32_16x16x32_bf16 v[8:11], v[196:199], v[168:171], v[8:11]
	s_waitcnt lgkmcnt(4)
	v_mfma_f32_16x16x32_bf16 v[12:15], v[200:203], v[168:171], v[12:15]
	s_waitcnt lgkmcnt(3)
	v_mfma_f32_16x16x32_bf16 v[16:19], v[188:191], v[172:175], v[16:19]
	v_mfma_f32_16x16x32_bf16 v[20:23], v[192:195], v[172:175], v[20:23]
	v_mfma_f32_16x16x32_bf16 v[24:27], v[196:199], v[172:175], v[24:27]
	v_mfma_f32_16x16x32_bf16 v[28:31], v[200:203], v[172:175], v[28:31]
	s_waitcnt lgkmcnt(2)
	v_mfma_f32_16x16x32_bf16 v[32:35], v[188:191], v[176:179], v[32:35]
	v_mfma_f32_16x16x32_bf16 v[36:39], v[192:195], v[176:179], v[36:39]
	v_mfma_f32_16x16x32_bf16 v[40:43], v[196:199], v[176:179], v[40:43]
	v_mfma_f32_16x16x32_bf16 v[44:47], v[200:203], v[176:179], v[44:47]
	s_waitcnt lgkmcnt(1)
	v_mfma_f32_16x16x32_bf16 v[48:51], v[188:191], v[180:183], v[48:51]
	v_mfma_f32_16x16x32_bf16 v[52:55], v[192:195], v[180:183], v[52:55]
	v_mfma_f32_16x16x32_bf16 v[56:59], v[196:199], v[180:183], v[56:59]
	v_mfma_f32_16x16x32_bf16 v[60:63], v[200:203], v[180:183], v[60:63]
	s_add_u32 s2, s2, 0x80
	s_addc_u32 s3, s3, 0
	s_add_u32 s6, s6, 0x80
	s_addc_u32 s7, s7, 0
	s_waitcnt lgkmcnt(0)
	v_mfma_f32_16x16x32_bf16 v[64:67], v[188:191], v[184:187], v[64:67]
	v_mfma_f32_16x16x32_bf16 v[68:71], v[192:195], v[184:187], v[68:71]
	v_mfma_f32_16x16x32_bf16 v[72:75], v[196:199], v[184:187], v[72:75]
	v_mfma_f32_16x16x32_bf16 v[76:79], v[200:203], v[184:187], v[76:79]
	s_cmp_eq_u32 s12, 1
	s_cselect_b32 s2, s20, s2
	s_cselect_b32 s3, s21, s3
	s_cselect_b32 s6, s22, s6
	s_cselect_b32 s7, s23, s7
	s_waitcnt vmcnt(0)
	s_barrier
	ds_read_b128 v[80:83], v204 offset:53504
	ds_read_b128 v[100:103], v206 offset:36864
	ds_read_b128 v[104:107], v206 offset:38912
	ds_read_b128 v[108:111], v206 offset:40960
	ds_read_b128 v[112:115], v206 offset:43008
	ds_read_b128 v[84:87], v204 offset:55552
	ds_read_b128 v[88:91], v204 offset:57600
	ds_read_b128 v[92:95], v204 offset:59648
	ds_read_b128 v[96:99], v204 offset:61696
	s_add_u32 m0, s13, 0x0
	s_waitcnt lgkmcnt(7)
	v_mfma_f32_16x16x32_bf16 v[0:3], v[100:103], v[80:83], v[0:3]
	global_load_lds_dwordx4 v208, s[2:3]
	s_add_u32 m0, s13, 0x1000
	s_waitcnt lgkmcnt(6)
	v_mfma_f32_16x16x32_bf16 v[4:7], v[104:107], v[80:83], v[4:7]
	global_load_lds_dwordx4 v209, s[2:3]
	s_add_u32 m0, s13, 0x2000
	s_waitcnt lgkmcnt(5)
	v_mfma_f32_16x16x32_bf16 v[8:11], v[108:111], v[80:83], v[8:11]
	global_load_lds_dwordx4 v210, s[2:3]
	s_add_u32 m0, s13, 0x3000
	s_waitcnt lgkmcnt(4)
	v_mfma_f32_16x16x32_bf16 v[12:15], v[112:115], v[80:83], v[12:15]
	global_load_lds_dwordx4 v211, s[2:3]
	s_add_u32 m0, s13, 0x4000
	ds_read_b128 v[168:171], v205 offset:53504
	ds_read_b128 v[188:191], v207 offset:36864
	ds_read_b128 v[192:195], v207 offset:38912
	ds_read_b128 v[196:199], v207 offset:40960
	ds_read_b128 v[200:203], v207 offset:43008
	s_waitcnt lgkmcnt(8)
	v_mfma_f32_16x16x32_bf16 v[16:19], v[100:103], v[84:87], v[16:19]
	global_load_lds_dwordx4 v212, s[2:3]
	s_add_u32 m0, s13, 0x5000
	v_mfma_f32_16x16x32_bf16 v[20:23], v[104:107], v[84:87], v[20:23]
	global_load_lds_dwordx4 v213, s[6:7]
	s_add_u32 m0, s13, 0x6000
	v_mfma_f32_16x16x32_bf16 v[24:27], v[108:111], v[84:87], v[24:27]
	global_load_lds_dwordx4 v214, s[6:7]
	s_add_u32 m0, s13, 0x7000
	v_mfma_f32_16x16x32_bf16 v[28:31], v[112:115], v[84:87], v[28:31]
	global_load_lds_dwordx4 v215, s[6:7]
	s_add_u32 m0, s13, 0x8000
	ds_read_b128 v[172:175], v205 offset:55552
	ds_read_b128 v[176:179], v205 offset:57600
	ds_read_b128 v[180:183], v205 offset:59648
	ds_read_b128 v[184:187], v205 offset:61696
	s_waitcnt lgkmcnt(11)
	v_mfma_f32_16x16x32_bf16 v[32:35], v[100:103], v[88:91], v[32:35]
	global_load_lds_dwordx4 v216, s[6:7]
	v_mfma_f32_16x16x32_bf16 v[36:39], v[104:107], v[88:91], v[36:39]
	v_mfma_f32_16x16x32_bf16 v[40:43], v[108:111], v[88:91], v[40:43]
	v_mfma_f32_16x16x32_bf16 v[44:47], v[112:115], v[88:91], v[44:47]
	s_waitcnt lgkmcnt(10)
	v_mfma_f32_16x16x32_bf16 v[48:51], v[100:103], v[92:95], v[48:51]
	v_mfma_f32_16x16x32_bf16 v[52:55], v[104:107], v[92:95], v[52:55]
	v_mfma_f32_16x16x32_bf16 v[56:59], v[108:111], v[92:95], v[56:59]
	v_mfma_f32_16x16x32_bf16 v[60:63], v[112:115], v[92:95], v[60:63]
	s_waitcnt lgkmcnt(9)
	v_mfma_f32_16x16x32_bf16 v[64:67], v[100:103], v[96:99], v[64:67]
	v_mfma_f32_16x16x32_bf16 v[68:71], v[104:107], v[96:99], v[68:71]
	v_mfma_f32_16x16x32_bf16 v[72:75], v[108:111], v[96:99], v[72:75]
	v_mfma_f32_16x16x32_bf16 v[76:79], v[112:115], v[96:99], v[76:79]
	s_waitcnt lgkmcnt(7)
	v_mfma_f32_16x16x32_bf16 v[0:3], v[188:191], v[168:171], v[0:3]
	s_waitcnt lgkmcnt(6)
	v_mfma_f32_16x16x32_bf16 v[4:7], v[192:195], v[168:171], v[4:7]
	s_waitcnt lgkmcnt(5)
	v_mfma_f32_16x16x32_bf16 v[8:11], v[196:199], v[168:171], v[8:11]
	s_waitcnt lgkmcnt(4)
	v_mfma_f32_16x16x32_bf16 v[12:15], v[200:203], v[168:171], v[12:15]
	s_waitcnt lgkmcnt(3)
	v_mfma_f32_16x16x32_bf16 v[16:19], v[188:191], v[172:175], v[16:19]
	v_mfma_f32_16x16x32_bf16 v[20:23], v[192:195], v[172:175], v[20:23]
	v_mfma_f32_16x16x32_bf16 v[24:27], v[196:199], v[172:175], v[24:27]
	v_mfma_f32_16x16x32_bf16 v[28:31], v[200:203], v[172:175], v[28:31]
	s_waitcnt lgkmcnt(2)
	v_mfma_f32_16x16x32_bf16 v[32:35], v[188:191], v[176:179], v[32:35]
	v_mfma_f32_16x16x32_bf16 v[36:39], v[192:195], v[176:179], v[36:39]
	v_mfma_f32_16x16x32_bf16 v[40:43], v[196:199], v[176:179], v[40:43]
	v_mfma_f32_16x16x32_bf16 v[44:47], v[200:203], v[176:179], v[44:47]
	s_waitcnt lgkmcnt(1)
	v_mfma_f32_16x16x32_bf16 v[48:51], v[188:191], v[180:183], v[48:51]
	v_mfma_f32_16x16x32_bf16 v[52:55], v[192:195], v[180:183], v[52:55]
	v_mfma_f32_16x16x32_bf16 v[56:59], v[196:199], v[180:183], v[56:59]
	v_mfma_f32_16x16x32_bf16 v[60:63], v[200:203], v[180:183], v[60:63]
	s_add_u32 s2, s2, 0x80
	s_addc_u32 s3, s3, 0
	s_add_u32 s6, s6, 0x80
	s_addc_u32 s7, s7, 0
	s_waitcnt lgkmcnt(0)
	v_mfma_f32_16x16x32_bf16 v[64:67], v[188:191], v[184:187], v[64:67]
	v_mfma_f32_16x16x32_bf16 v[68:71], v[192:195], v[184:187], v[68:71]
	v_mfma_f32_16x16x32_bf16 v[72:75], v[196:199], v[184:187], v[72:75]
	v_mfma_f32_16x16x32_bf16 v[76:79], v[200:203], v[184:187], v[76:79]
	s_sub_u32 s12, s12, 1
	s_cmp_lg_u32 s12, 0
	s_cbranch_scc1 .Lgdn1_pair
	s_and_b32 s4, s10, 7
	s_lshl_b32 s4, s4, 3
	s_bfe_u32 s14, s10, 0x30003
	s_or_b32 s14, s14, s4
	s_lshr_b32 s15, s10, 6
	s_mul_i32 s4, s14, 0x50000
	s_lshl_b32 s32, s15, 8
	s_add_u32 s4, s4, s32
	s_add_u32 s8, s78, s4
	s_addc_u32 s9, s79, 0
	s_nop 7
	v_cvt_pk_bf16_f32 v80, v0, v1
	v_cvt_pk_bf16_f32 v81, v2, v3
	v_cvt_pk_bf16_f32 v82, v4, v5
	v_cvt_pk_bf16_f32 v83, v6, v7
	global_store_dwordx4 v217, v[80:83], s[8:9]
	v_cvt_pk_bf16_f32 v84, v8, v9
	v_cvt_pk_bf16_f32 v85, v10, v11
	v_cvt_pk_bf16_f32 v86, v12, v13
	v_cvt_pk_bf16_f32 v87, v14, v15
	global_store_dwordx4 v217, v[84:87], s[8:9] offset:64
	s_add_u32 s8, s8, 0x8000
	s_addc_u32 s9, s9, 0
	v_cvt_pk_bf16_f32 v88, v16, v17
	v_cvt_pk_bf16_f32 v89, v18, v19
	v_cvt_pk_bf16_f32 v90, v20, v21
	v_cvt_pk_bf16_f32 v91, v22, v23
	global_store_dwordx4 v217, v[88:91], s[8:9]
	v_cvt_pk_bf16_f32 v92, v24, v25
	v_cvt_pk_bf16_f32 v93, v26, v27
	v_cvt_pk_bf16_f32 v94, v28, v29
	v_cvt_pk_bf16_f32 v95, v30, v31
	global_store_dwordx4 v217, v[92:95], s[8:9] offset:64
	s_add_u32 s8, s8, 0x8000
	s_addc_u32 s9, s9, 0
	v_cvt_pk_bf16_f32 v96, v32, v33
	v_cvt_pk_bf16_f32 v97, v34, v35
	v_cvt_pk_bf16_f32 v98, v36, v37
	v_cvt_pk_bf16_f32 v99, v38, v39
	global_store_dwordx4 v217, v[96:99], s[8:9]
	v_cvt_pk_bf16_f32 v100, v40, v41
	v_cvt_pk_bf16_f32 v101, v42, v43
	v_cvt_pk_bf16_f32 v102, v44, v45
	v_cvt_pk_bf16_f32 v103, v46, v47
	global_store_dwordx4 v217, v[100:103], s[8:9] offset:64
	s_add_u32 s8, s8, 0x8000
	s_addc_u32 s9, s9, 0
	v_cvt_pk_bf16_f32 v104, v48, v49
	v_cvt_pk_bf16_f32 v105, v50, v51
	v_cvt_pk_bf16_f32 v106, v52, v53
	v_cvt_pk_bf16_f32 v107, v54, v55
	global_store_dwordx4 v217, v[104:107], s[8:9]
	v_cvt_pk_bf16_f32 v108, v56, v57
	v_cvt_pk_bf16_f32 v109, v58, v59
	v_cvt_pk_bf16_f32 v110, v60, v61
	v_cvt_pk_bf16_f32 v111, v62, v63
	global_store_dwordx4 v217, v[108:111], s[8:9] offset:64
	s_add_u32 s8, s8, 0x8000
	s_addc_u32 s9, s9, 0
	v_cvt_pk_bf16_f32 v112, v64, v65
	v_cvt_pk_bf16_f32 v113, v66, v67
	v_cvt_pk_bf16_f32 v114, v68, v69
	v_cvt_pk_bf16_f32 v115, v70, v71
	global_store_dwordx4 v217, v[112:115], s[8:9]
	v_cvt_pk_bf16_f32 v80, v72, v73
	v_cvt_pk_bf16_f32 v81, v74, v75
	v_cvt_pk_bf16_f32 v82, v76, v77
	v_cvt_pk_bf16_f32 v83, v78, v79
	global_store_dwordx4 v217, v[80:83], s[8:9] offset:64
	s_add_u32 s10, s10, s11
	s_cmp_lt_u32 s10, 0x200
	s_cbranch_scc1 .Lgdn1_tile
.Lgdn1_done:
	s_setprio 0
.LBB0_1061:
	v_readlane_b32 s2, v162, 36
	v_readlane_b32 s20, v162, 12
	s_add_i32 s35, s2, 13
	v_readlane_b32 s21, v162, 13
	s_cmp_ge_i32 s35, s21
	v_readlane_b32 s22, v162, 14
	v_readlane_b32 s23, v162, 15
	s_cbranch_scc1 .LBB0_1111
	s_waitcnt vmcnt(0)
	v_readlane_b32 s4, v163, 17
	v_readlane_b32 s5, v163, 18
	s_barrier
	s_and_saveexec_b64 s[2:3], s[4:5]
	s_cbranch_execz .LBB0_1110
	s_waitcnt vmcnt(0) expcnt(0) lgkmcnt(0)
	ds_read_b32 v2, v117 offset:53248
	ds_read_b32 v0, v117 offset:53252
	s_waitcnt lgkmcnt(1)
	v_cmp_ne_u32_e32 vcc, 0, v2
	s_cbranch_vccnz .LBB0_1078
	s_mov_b32 s36, 1
	s_branch .LBB0_1066

	.amdhsa_kernel _Z2mk1Pii
		.amdhsa_group_segment_fixed_size 73984
		.amdhsa_private_segment_fixed_size 0
		.amdhsa_kernarg_size 664
		.amdhsa_user_sgpr_count 2
		.amdhsa_user_sgpr_dispatch_ptr 0
		.amdhsa_user_sgpr_queue_ptr 0
		.amdhsa_user_sgpr_kernarg_segment_ptr 1
		.amdhsa_user_sgpr_dispatch_id 0
		.amdhsa_user_sgpr_kernarg_preload_length 0
		.amdhsa_user_sgpr_kernarg_preload_offset 0
		.amdhsa_user_sgpr_private_segment_size 0
		.amdhsa_uses_dynamic_stack 0
		.amdhsa_enable_private_segment 0
		.amdhsa_system_sgpr_workgroup_id_x 1
		.amdhsa_system_sgpr_workgroup_id_y 0
		.amdhsa_system_sgpr_workgroup_id_z 0
		.amdhsa_system_sgpr_workgroup_info 0
		.amdhsa_system_vgpr_workitem_id 2
		.amdhsa_next_free_vgpr 256
		.amdhsa_next_free_sgpr 100
		.amdhsa_accum_offset 256
		.amdhsa_reserve_vcc 1
		.amdhsa_float_round_mode_32 0
		.amdhsa_float_round_mode_16_64 0
		.amdhsa_float_denorm_mode_32 3
		.amdhsa_float_denorm_mode_16_64 3
		.amdhsa_dx10_clamp 1
		.amdhsa_ieee_mode 1
		.amdhsa_fp16_overflow 0
		.amdhsa_tg_split 0
		.amdhsa_exception_fp_ieee_invalid_op 0
		.amdhsa_exception_fp_denorm_src 0
		.amdhsa_exception_fp_ieee_div_zero 0
		.amdhsa_exception_fp_ieee_overflow 0
		.amdhsa_exception_fp_ieee_underflow 0
		.amdhsa_exception_fp_ieee_inexact 0
		.amdhsa_exception_int_div_zero 0
	.end_amdhsa_kernel

amdhsa.kernels:
  - .agpr_count:     0
    .args:
      - .offset:         0
        .size:           400
        .value_kind:     by_value
      - .offset:         400
        .size:           4
        .value_kind:     by_value
      - .offset:         404
        .size:           4
        .value_kind:     by_value
      - .offset:         408
        .size:           4
        .value_kind:     hidden_block_count_x
      - .offset:         412
        .size:           4
        .value_kind:     hidden_block_count_y
      - .offset:         416
        .size:           4
        .value_kind:     hidden_block_count_z
      - .offset:         420
        .size:           2
        .value_kind:     hidden_group_size_x
      - .offset:         422
        .size:           2
        .value_kind:     hidden_group_size_y
      - .offset:         424
        .size:           2
        .value_kind:     hidden_group_size_z
      - .offset:         426
        .size:           2
        .value_kind:     hidden_remainder_x
      - .offset:         428
        .size:           2
        .value_kind:     hidden_remainder_y
      - .offset:         430
        .size:           2
        .value_kind:     hidden_remainder_z
      - .offset:         448
        .size:           8
        .value_kind:     hidden_global_offset_x
      - .offset:         456
        .size:           8
        .value_kind:     hidden_global_offset_y
      - .offset:         464
        .size:           8
        .value_kind:     hidden_global_offset_z
      - .offset:         472
        .size:           2
        .value_kind:     hidden_grid_dims
      - .offset:         496
        .size:           8
        .value_kind:     hidden_multigrid_sync_arg
    .group_segment_fixed_size: 73984
    .kernarg_segment_align: 8
    .kernarg_segment_size: 664
    .language:       OpenCL C
    .language_version:
      - 2
      - 0
    .max_flat_workgroup_size: 256
    .name:           _Z2mk1Pii
    .private_segment_fixed_size: 0
    .sgpr_count:     106
    .sgpr_spill_count: 187
    .symbol:         _Z2mk1Pii.kd
    .uniform_work_group_size: 1
    .uses_dynamic_stack: false
    .vgpr_count:     256
    .vgpr_spill_count: 0
    .wavefront_size: 64
